# v69 + GEMM K-loops: redundant post-barrier lgkmcnt(0) removed, vmcnt/lgkmcnt waits merged
# speedup vs baseline: 1.0164x; 1.0164x over previous
; #define PG8_STAGE(bufoff, gbase, voff) do { _Pragma("unroll") for (int _i = 0; _i < 2; ++_i) \
;         __builtin_amdgcn_global_load_lds((const unsigned*)((const char*)(gbase) + (voff)[_i]), (PG8_LAS unsigned*)(lds + (bufoff) + ldsw + _i * 8192), 16, 0, 0); } while (0)
; #define PG8_LDA(dst, b, h) do { _Pragma("unroll") for (int m = 0; m < 4; ++m) _Pragma("unroll") for (int k = 0; k < 2; ++k) dst[m][k] = *(const PG8_LAS bf16x8*)(lds + PG8_SA(b, h) + aoff + m * 2048 + k * 1024); } while (0)
; #define PG8_LDB(dst, b, h) do { _Pragma("unroll") for (int n = 0; n < 2; ++n) _Pragma("unroll") for (int k = 0; k < 2; ++k) dst[n][k] = *(const PG8_LAS bf16x8*)(lds + PG8_SB(b, h) + boff + n * 2048 + k * 1024); } while (0)
; #define PG8_MMA(ai, bj, At, Bt) do { __builtin_amdgcn_s_setprio(1); _Pragma("unroll") for (int m = 0; m < 4; ++m) _Pragma("unroll") for (int n = 0; n < 2; ++n) _Pragma("unroll") for (int k = 0; k < 2; ++k) \
;         acc[ai][bj][m][n] = __builtin_amdgcn_mfma_f32_16x16x32_bf16(Bt[n][k], At[m][k], acc[ai][bj][m][n], 0, 0, 0); __builtin_amdgcn_s_setprio(0); } while (0)
; #define PG8_WAIT_V(n) asm volatile("s_waitcnt vmcnt(" #n ")" ::: "memory")
; #define PG8_BAR __builtin_amdgcn_s_barrier()
; template <class Epi, class Sched, bool ALIGN_EPI = false, bool SP2 = false>
; __device__ __forceinline__ void gemm_phase(PG8_LAS unsigned char* lds, const Gemm g, const Sched& S, const Epi& E) {
;     ...
;         for (int t = 0; t < nt; t += 2) {
;             const bool last = (t == nt - 2);
;             const char* a1 = cA + (size_t)(t + 1) * kstep;
;             const char* a2 = last ? nA : cA + (size_t)(t + 2) * kstep; const char* b2 = last ? nB : cB + (size_t)(t + 2) * kstep;
;             const char* a3 = a2 + kstep; const char* b3 = b2 + kstep;
;             if (last && has_next) S.a_ready(nxt);
;             if constexpr (SP2) {
;             PG8_LDB(B0, 0, 0); PG8_LDB(B1, 0, 1); PG8_SCHED; PG8_LDA(At, 0, 0); PG8_STAGE(PG8_SA(1, 1), a1 + hstep, voffA);
;             PG8_WAIT_V(8); PG8_WAIT_L(0); PG8_BAR; PG8_MMA(0, 0, At, B0); PG8_MMA(0, 1, At, B1); PG8_BAR; PG8_SCHED;
;             PG8_LDA(At, 0, 1); PG8_STAGE(PG8_SB(0, 0), b2, voffB); PG8_STAGE(PG8_SB(0, 1), b2 + hstep, voffB); PG8_STAGE(PG8_SA(0, 0), a2, voffA);
;             PG8_WAIT_V(8); PG8_WAIT_L(0); PG8_BAR; PG8_MMA(1, 0, At, B0); PG8_MMA(1, 1, At, B1); PG8_BAR; PG8_SCHED;
.LBB0_100:
	s_add_u32 s28, s8, 0xfffc0080
	s_addc_u32 s29, s9, -1
	s_add_i32 s53, 0, 0x10000
	s_cmp_eq_u32 s45, 12
	s_cselect_b32 s31, s3, s29
	s_cselect_b32 s30, s7, s28
	s_cselect_b32 s29, s11, s44
	s_cselect_b32 s28, s21, s23
	s_add_i32 s56, 0, 0x14000
	v_add_u32_e32 v144, s53, v204
	v_add_u32_e32 v160, s56, v204
	ds_read_b128 v[132:135], v144
	ds_read_b128 v[136:139], v144 offset:1024
	ds_read_b128 v[140:143], v144 offset:2048
	ds_read_b128 v[144:147], v144 offset:3072
	ds_read_b128 v[148:151], v160
	ds_read_b128 v[152:155], v160 offset:1024
	ds_read_b128 v[156:159], v160 offset:2048
	ds_read_b128 v[160:163], v160 offset:3072
	v_lshl_add_u64 v[194:195], s[8:9], 0, v[178:179]
	s_add_i32 m0, s42, 0xc000
	ds_read_b128 v[164:167], v205
	ds_read_b128 v[182:185], v205 offset:1024
	ds_read_b128 v[186:189], v205 offset:2048
	ds_read_b128 v[190:193], v205 offset:3072
	ds_read_b128 v[208:211], v205 offset:4096
	ds_read_b128 v[212:215], v205 offset:5120
	ds_read_b128 v[216:219], v205 offset:6144
	ds_read_b128 v[220:223], v205 offset:7168
	global_load_lds_dwordx4 v[194:195], off
	s_add_i32 m0, s42, 0xe000
	v_lshl_add_u64 v[194:195], s[8:9], 0, v[180:181]
	global_load_lds_dwordx4 v[194:195], off
	s_waitcnt vmcnt(8) lgkmcnt(0)
	s_barrier
	s_setprio 1
	v_mfma_f32_16x16x32_bf16 v[128:131], v[132:135], v[164:167], v[128:131]
	v_mfma_f32_16x16x32_bf16 v[124:127], v[140:143], v[164:167], v[124:127]
	v_mfma_f32_16x16x32_bf16 v[112:115], v[132:135], v[186:189], v[112:115]
	v_mfma_f32_16x16x32_bf16 v[108:111], v[140:143], v[186:189], v[108:111]
	v_mfma_f32_16x16x32_bf16 v[96:99], v[132:135], v[208:211], v[96:99]
	v_mfma_f32_16x16x32_bf16 v[92:95], v[140:143], v[208:211], v[92:95]
	v_mfma_f32_16x16x32_bf16 v[80:83], v[132:135], v[216:219], v[80:83]
	v_mfma_f32_16x16x32_bf16 v[76:79], v[140:143], v[216:219], v[76:79]
	v_mfma_f32_16x16x32_bf16 v[128:131], v[136:139], v[182:185], v[128:131]
	v_mfma_f32_16x16x32_bf16 v[124:127], v[144:147], v[182:185], v[124:127]
	v_mfma_f32_16x16x32_bf16 v[112:115], v[136:139], v[190:193], v[112:115]
	v_mfma_f32_16x16x32_bf16 v[108:111], v[144:147], v[190:193], v[108:111]
	v_mfma_f32_16x16x32_bf16 v[96:99], v[136:139], v[212:215], v[96:99]
	v_mfma_f32_16x16x32_bf16 v[92:95], v[144:147], v[212:215], v[92:95]
	v_mfma_f32_16x16x32_bf16 v[80:83], v[136:139], v[220:223], v[80:83]
	v_mfma_f32_16x16x32_bf16 v[76:79], v[144:147], v[220:223], v[76:79]
	s_setprio 0
	s_setprio 1
	v_mfma_f32_16x16x32_bf16 v[120:123], v[148:151], v[164:167], v[120:123]
	v_mfma_f32_16x16x32_bf16 v[116:119], v[156:159], v[164:167], v[116:119]
	v_mfma_f32_16x16x32_bf16 v[104:107], v[148:151], v[186:189], v[104:107]
	v_mfma_f32_16x16x32_bf16 v[100:103], v[156:159], v[186:189], v[100:103]
	v_mfma_f32_16x16x32_bf16 v[88:91], v[148:151], v[208:211], v[88:91]
	v_mfma_f32_16x16x32_bf16 v[84:87], v[156:159], v[208:211], v[84:87]
	v_mfma_f32_16x16x32_bf16 v[72:75], v[148:151], v[216:219], v[72:75]
	v_mfma_f32_16x16x32_bf16 v[68:71], v[156:159], v[216:219], v[68:71]
	v_mfma_f32_16x16x32_bf16 v[120:123], v[152:155], v[182:185], v[120:123]
	v_mfma_f32_16x16x32_bf16 v[116:119], v[160:163], v[182:185], v[116:119]
	v_mfma_f32_16x16x32_bf16 v[104:107], v[152:155], v[190:193], v[104:107]
	v_mfma_f32_16x16x32_bf16 v[100:103], v[160:163], v[190:193], v[100:103]
	v_mfma_f32_16x16x32_bf16 v[88:91], v[152:155], v[212:215], v[88:91]
	v_mfma_f32_16x16x32_bf16 v[84:87], v[160:163], v[212:215], v[84:87]
	v_mfma_f32_16x16x32_bf16 v[72:75], v[152:155], v[220:223], v[72:75]
	v_mfma_f32_16x16x32_bf16 v[68:71], v[160:163], v[220:223], v[68:71]
	s_setprio 0
	s_barrier
	s_add_i32 s53, s53, s41
	v_lshl_add_u64 v[194:195], s[28:29], 0, v[168:169]
	s_mov_b32 m0, s53
	ds_read_b128 v[164:167], v205 offset:16384
	ds_read_b128 v[182:185], v205 offset:17408
	ds_read_b128 v[186:189], v205 offset:18432
	ds_read_b128 v[190:193], v205 offset:19456
	ds_read_b128 v[208:211], v205 offset:20480
	ds_read_b128 v[212:215], v205 offset:21504
	ds_read_b128 v[216:219], v205 offset:22528
	ds_read_b128 v[220:223], v205 offset:23552
	global_load_lds_dwordx4 v[194:195], off
	s_add_i32 m0, s53, 0x2000
	s_add_u32 s54, s28, 0x40000
	v_lshl_add_u64 v[202:203], s[28:29], 0, v[172:173]
	s_addc_u32 s55, s29, 0
	s_add_i32 s53, s56, s41
	global_load_lds_dwordx4 v[202:203], off
	v_lshl_add_u64 v[224:225], s[54:55], 0, v[168:169]
	s_mov_b32 m0, s53
	v_lshl_add_u64 v[226:227], s[30:31], 0, v[170:171]
	global_load_lds_dwordx4 v[224:225], off
	s_add_i32 m0, s53, 0x2000
	v_lshl_add_u64 v[224:225], s[54:55], 0, v[172:173]
	global_load_lds_dwordx4 v[224:225], off
	s_mov_b32 m0, s42
	v_lshl_add_u64 v[224:225], s[30:31], 0, v[0:1]
	global_load_lds_dwordx4 v[224:225], off
	s_mov_b32 m0, s43
	s_nop 0
	global_load_lds_dwordx4 v[226:227], off
	s_waitcnt vmcnt(8) lgkmcnt(0)
	s_barrier
; #define PG8_STAGE(bufoff, gbase, voff) do { _Pragma("unroll") for (int _i = 0; _i < 2; ++_i) \
;         __builtin_amdgcn_global_load_lds((const unsigned*)((const char*)(gbase) + (voff)[_i]), (PG8_LAS unsigned*)(lds + (bufoff) + ldsw + _i * 8192), 16, 0, 0); } while (0)
; #define PG8_LDA(dst, b, h) do { _Pragma("unroll") for (int m = 0; m < 4; ++m) _Pragma("unroll") for (int k = 0; k < 2; ++k) dst[m][k] = *(const PG8_LAS bf16x8*)(lds + PG8_SA(b, h) + aoff + m * 2048 + k * 1024); } while (0)
; #define PG8_LDB(dst, b, h) do { _Pragma("unroll") for (int n = 0; n < 2; ++n) _Pragma("unroll") for (int k = 0; k < 2; ++k) dst[n][k] = *(const PG8_LAS bf16x8*)(lds + PG8_SB(b, h) + boff + n * 2048 + k * 1024); } while (0)
; #define PG8_MMA(ai, bj, At, Bt) do { __builtin_amdgcn_s_setprio(1); _Pragma("unroll") for (int m = 0; m < 4; ++m) _Pragma("unroll") for (int n = 0; n < 2; ++n) _Pragma("unroll") for (int k = 0; k < 2; ++k) \
;         acc[ai][bj][m][n] = __builtin_amdgcn_mfma_f32_16x16x32_bf16(Bt[n][k], At[m][k], acc[ai][bj][m][n], 0, 0, 0); __builtin_amdgcn_s_setprio(0); } while (0)
; #define PG8_WAIT_V(n) asm volatile("s_waitcnt vmcnt(" #n ")" ::: "memory")
; #define PG8_WAIT_L(n) asm volatile("s_waitcnt lgkmcnt(" #n ")" ::: "memory")
; #define PG8_BAR __builtin_amdgcn_s_barrier()
; #define PG8_SCHED __builtin_amdgcn_sched_barrier(0)
; template <class Epi, class Sched, bool ALIGN_EPI = false, bool SP2 = false>
; __device__ __forceinline__ void gemm_phase(PG8_LAS unsigned char* lds, const Gemm g, const Sched& S, const Epi& E) {
;     ...
;             PG8_WAIT_V(8); PG8_WAIT_L(0); PG8_BAR; PG8_MMA(1, 0, At, B0); PG8_MMA(1, 1, At, B1); PG8_BAR; PG8_SCHED;
;             PG8_LDB(B0, 1, 0); PG8_LDB(B1, 1, 1); PG8_SCHED; PG8_LDA(At, 1, 0); PG8_STAGE(PG8_SA(0, 1), a2 + hstep, voffA);
;             PG8_WAIT_V(8); PG8_WAIT_L(0); PG8_BAR; PG8_MMA(0, 0, At, B0); PG8_MMA(0, 1, At, B1); PG8_BAR; PG8_SCHED;
	s_setprio 1
	v_mfma_f32_16x16x32_bf16 v[64:67], v[132:135], v[164:167], v[64:67]
	v_mfma_f32_16x16x32_bf16 v[60:63], v[140:143], v[164:167], v[60:63]
	v_mfma_f32_16x16x32_bf16 v[48:51], v[132:135], v[186:189], v[48:51]
	v_mfma_f32_16x16x32_bf16 v[44:47], v[140:143], v[186:189], v[44:47]
	v_mfma_f32_16x16x32_bf16 v[32:35], v[132:135], v[208:211], v[32:35]
	v_mfma_f32_16x16x32_bf16 v[28:31], v[140:143], v[208:211], v[28:31]
	v_mfma_f32_16x16x32_bf16 v[16:19], v[132:135], v[216:219], v[16:19]
	v_mfma_f32_16x16x32_bf16 v[12:15], v[140:143], v[216:219], v[12:15]
	v_mfma_f32_16x16x32_bf16 v[64:67], v[136:139], v[182:185], v[64:67]
	v_mfma_f32_16x16x32_bf16 v[60:63], v[144:147], v[182:185], v[60:63]
	v_mfma_f32_16x16x32_bf16 v[48:51], v[136:139], v[190:193], v[48:51]
	v_mfma_f32_16x16x32_bf16 v[44:47], v[144:147], v[190:193], v[44:47]
	v_mfma_f32_16x16x32_bf16 v[32:35], v[136:139], v[212:215], v[32:35]
	v_mfma_f32_16x16x32_bf16 v[28:31], v[144:147], v[212:215], v[28:31]
	v_mfma_f32_16x16x32_bf16 v[16:19], v[136:139], v[220:223], v[16:19]
	v_mfma_f32_16x16x32_bf16 v[12:15], v[144:147], v[220:223], v[12:15]
	s_setprio 0
	s_setprio 1
	v_mfma_f32_16x16x32_bf16 v[56:59], v[148:151], v[164:167], v[56:59]
	v_mfma_f32_16x16x32_bf16 v[52:55], v[156:159], v[164:167], v[52:55]
	v_mfma_f32_16x16x32_bf16 v[40:43], v[148:151], v[186:189], v[40:43]
	v_mfma_f32_16x16x32_bf16 v[36:39], v[156:159], v[186:189], v[36:39]
	v_mfma_f32_16x16x32_bf16 v[24:27], v[148:151], v[208:211], v[24:27]
	v_mfma_f32_16x16x32_bf16 v[20:23], v[156:159], v[208:211], v[20:23]
	v_mfma_f32_16x16x32_bf16 v[8:11], v[148:151], v[216:219], v[8:11]
	v_mfma_f32_16x16x32_bf16 v[4:7], v[156:159], v[216:219], v[4:7]
	v_mfma_f32_16x16x32_bf16 v[56:59], v[152:155], v[182:185], v[56:59]
	v_mfma_f32_16x16x32_bf16 v[52:55], v[160:163], v[182:185], v[52:55]
	v_mfma_f32_16x16x32_bf16 v[40:43], v[152:155], v[190:193], v[40:43]
	v_mfma_f32_16x16x32_bf16 v[36:39], v[160:163], v[190:193], v[36:39]
	v_mfma_f32_16x16x32_bf16 v[24:27], v[152:155], v[212:215], v[24:27]
	v_mfma_f32_16x16x32_bf16 v[20:23], v[160:163], v[212:215], v[20:23]
	v_mfma_f32_16x16x32_bf16 v[8:11], v[152:155], v[220:223], v[8:11]
	v_mfma_f32_16x16x32_bf16 v[4:7], v[160:163], v[220:223], v[4:7]
	s_setprio 0
	s_barrier
	s_add_i32 s53, 0, 0x18000
	s_add_i32 s54, 0, 0x1c000
	v_add_u32_e32 v144, s53, v204
	v_add_u32_e32 v160, s54, v204
	ds_read_b128 v[132:135], v144
	ds_read_b128 v[136:139], v144 offset:1024
	ds_read_b128 v[140:143], v144 offset:2048
	ds_read_b128 v[144:147], v144 offset:3072
	ds_read_b128 v[148:151], v160
	ds_read_b128 v[152:155], v160 offset:1024
	ds_read_b128 v[156:159], v160 offset:2048
	ds_read_b128 v[160:163], v160 offset:3072
	s_add_u32 s30, s30, 0x40000
	s_addc_u32 s31, s31, 0
	s_mov_b32 m0, s46
	v_lshl_add_u64 v[228:229], s[30:31], 0, v[0:1]
	ds_read_b128 v[164:167], v205 offset:32768
	ds_read_b128 v[182:185], v205 offset:33792
	ds_read_b128 v[186:189], v205 offset:34816
	ds_read_b128 v[190:193], v205 offset:35840
	ds_read_b128 v[208:211], v205 offset:36864
	ds_read_b128 v[212:215], v205 offset:37888
	ds_read_b128 v[216:219], v205 offset:38912
	ds_read_b128 v[220:223], v205 offset:39936
	global_load_lds_dwordx4 v[228:229], off
	s_mov_b32 m0, s47
	v_lshl_add_u64 v[228:229], s[30:31], 0, v[170:171]
	global_load_lds_dwordx4 v[228:229], off
	s_waitcnt vmcnt(8) lgkmcnt(0)
	s_barrier
	s_setprio 1
	v_mfma_f32_16x16x32_bf16 v[128:131], v[132:135], v[164:167], v[128:131]
	v_mfma_f32_16x16x32_bf16 v[124:127], v[140:143], v[164:167], v[124:127]
	v_mfma_f32_16x16x32_bf16 v[112:115], v[132:135], v[186:189], v[112:115]
	v_mfma_f32_16x16x32_bf16 v[108:111], v[140:143], v[186:189], v[108:111]
	v_mfma_f32_16x16x32_bf16 v[96:99], v[132:135], v[208:211], v[96:99]
	v_mfma_f32_16x16x32_bf16 v[92:95], v[140:143], v[208:211], v[92:95]
	v_mfma_f32_16x16x32_bf16 v[80:83], v[132:135], v[216:219], v[80:83]
	v_mfma_f32_16x16x32_bf16 v[76:79], v[140:143], v[216:219], v[76:79]
	v_mfma_f32_16x16x32_bf16 v[128:131], v[136:139], v[182:185], v[128:131]
	v_mfma_f32_16x16x32_bf16 v[124:127], v[144:147], v[182:185], v[124:127]
	v_mfma_f32_16x16x32_bf16 v[112:115], v[136:139], v[190:193], v[112:115]
	v_mfma_f32_16x16x32_bf16 v[108:111], v[144:147], v[190:193], v[108:111]
	v_mfma_f32_16x16x32_bf16 v[96:99], v[136:139], v[212:215], v[96:99]
	v_mfma_f32_16x16x32_bf16 v[92:95], v[144:147], v[212:215], v[92:95]
	v_mfma_f32_16x16x32_bf16 v[80:83], v[136:139], v[220:223], v[80:83]
	v_mfma_f32_16x16x32_bf16 v[76:79], v[144:147], v[220:223], v[76:79]
	s_setprio 0
	s_setprio 1
	v_mfma_f32_16x16x32_bf16 v[120:123], v[148:151], v[164:167], v[120:123]
	v_mfma_f32_16x16x32_bf16 v[116:119], v[156:159], v[164:167], v[116:119]
	v_mfma_f32_16x16x32_bf16 v[104:107], v[148:151], v[186:189], v[104:107]
	v_mfma_f32_16x16x32_bf16 v[100:103], v[156:159], v[186:189], v[100:103]
	v_mfma_f32_16x16x32_bf16 v[88:91], v[148:151], v[208:211], v[88:91]
	v_mfma_f32_16x16x32_bf16 v[84:87], v[156:159], v[208:211], v[84:87]
	v_mfma_f32_16x16x32_bf16 v[72:75], v[148:151], v[216:219], v[72:75]
	v_mfma_f32_16x16x32_bf16 v[68:71], v[156:159], v[216:219], v[68:71]
	v_mfma_f32_16x16x32_bf16 v[120:123], v[152:155], v[182:185], v[120:123]
	v_mfma_f32_16x16x32_bf16 v[116:119], v[160:163], v[182:185], v[116:119]
	v_mfma_f32_16x16x32_bf16 v[104:107], v[152:155], v[190:193], v[104:107]
	v_mfma_f32_16x16x32_bf16 v[100:103], v[160:163], v[190:193], v[100:103]
	v_mfma_f32_16x16x32_bf16 v[88:91], v[152:155], v[212:215], v[88:91]
	v_mfma_f32_16x16x32_bf16 v[84:87], v[160:163], v[212:215], v[84:87]
	v_mfma_f32_16x16x32_bf16 v[72:75], v[152:155], v[220:223], v[72:75]
	v_mfma_f32_16x16x32_bf16 v[68:71], v[160:163], v[220:223], v[68:71]
	s_setprio 0
	s_barrier
; #define PG8_STAGE(bufoff, gbase, voff) do { _Pragma("unroll") for (int _i = 0; _i < 2; ++_i) \
;         __builtin_amdgcn_global_load_lds((const unsigned*)((const char*)(gbase) + (voff)[_i]), (PG8_LAS unsigned*)(lds + (bufoff) + ldsw + _i * 8192), 16, 0, 0); } while (0)
; #define PG8_LDA(dst, b, h) do { _Pragma("unroll") for (int m = 0; m < 4; ++m) _Pragma("unroll") for (int k = 0; k < 2; ++k) dst[m][k] = *(const PG8_LAS bf16x8*)(lds + PG8_SA(b, h) + aoff + m * 2048 + k * 1024); } while (0)
; #define PG8_MMA(ai, bj, At, Bt) do { __builtin_amdgcn_s_setprio(1); _Pragma("unroll") for (int m = 0; m < 4; ++m) _Pragma("unroll") for (int n = 0; n < 2; ++n) _Pragma("unroll") for (int k = 0; k < 2; ++k) \
;         acc[ai][bj][m][n] = __builtin_amdgcn_mfma_f32_16x16x32_bf16(Bt[n][k], At[m][k], acc[ai][bj][m][n], 0, 0, 0); __builtin_amdgcn_s_setprio(0); } while (0)
; #define PG8_WAIT_V(n) asm volatile("s_waitcnt vmcnt(" #n ")" ::: "memory")
; #define PG8_WAIT_L(n) asm volatile("s_waitcnt lgkmcnt(" #n ")" ::: "memory")
; #define PG8_BAR __builtin_amdgcn_s_barrier()
; #define PG8_SCHED __builtin_amdgcn_sched_barrier(0)
; template <class Epi, class Sched, bool ALIGN_EPI = false, bool SP2 = false>
; __device__ __forceinline__ void gemm_phase(PG8_LAS unsigned char* lds, const Gemm g, const Sched& S, const Epi& E) {
;     ...
;             PG8_LDA(At, 1, 1); PG8_STAGE(PG8_SB(1, 0), b3, voffB); PG8_STAGE(PG8_SB(1, 1), b3 + hstep, voffB); PG8_STAGE(PG8_SA(1, 0), a3, voffA);
;             PG8_WAIT_V(8); PG8_WAIT_L(0); PG8_BAR; PG8_MMA(1, 0, At, B0); PG8_MMA(1, 1, At, B1); PG8_BAR; PG8_SCHED;
;     ...
;         if constexpr (ALIGN_EPI) { if (wr == 0) PG8_BAR; }
	s_add_i32 s30, s53, s41
	v_lshl_add_u64 v[194:195], v[194:195], 0, s[82:83]
	s_mov_b32 m0, s30
	ds_read_b128 v[164:167], v205 offset:49152
	ds_read_b128 v[182:185], v205 offset:50176
	ds_read_b128 v[186:189], v205 offset:51200
	ds_read_b128 v[190:193], v205 offset:52224
	ds_read_b128 v[208:211], v205 offset:53248
	ds_read_b128 v[212:215], v205 offset:54272
	ds_read_b128 v[216:219], v205 offset:55296
	ds_read_b128 v[220:223], v205 offset:56320
	global_load_lds_dwordx4 v[194:195], off
	s_add_i32 m0, s30, 0x2000
	s_add_u32 s28, s28, 0x40080
	v_lshl_add_u64 v[194:195], v[202:203], 0, s[82:83]
	s_addc_u32 s29, s29, 0
	s_add_i32 s30, s54, s41
	global_load_lds_dwordx4 v[194:195], off
	s_mov_b32 m0, s30
	v_lshl_add_u64 v[194:195], s[28:29], 0, v[168:169]
	global_load_lds_dwordx4 v[194:195], off
	s_add_i32 m0, s30, 0x2000
	v_lshl_add_u64 v[194:195], s[28:29], 0, v[172:173]
	global_load_lds_dwordx4 v[194:195], off
	s_mov_b32 m0, s50
	v_lshl_add_u64 v[194:195], v[224:225], 0, s[82:83]
	global_load_lds_dwordx4 v[194:195], off
	s_mov_b32 m0, s51
	v_lshl_add_u64 v[194:195], v[226:227], 0, s[82:83]
	global_load_lds_dwordx4 v[194:195], off
	s_waitcnt vmcnt(8) lgkmcnt(0)
	s_barrier
	s_setprio 1
	v_mfma_f32_16x16x32_bf16 v[64:67], v[132:135], v[164:167], v[64:67]
	v_mfma_f32_16x16x32_bf16 v[60:63], v[140:143], v[164:167], v[60:63]
	v_mfma_f32_16x16x32_bf16 v[48:51], v[132:135], v[186:189], v[48:51]
	v_mfma_f32_16x16x32_bf16 v[44:47], v[140:143], v[186:189], v[44:47]
	v_mfma_f32_16x16x32_bf16 v[32:35], v[132:135], v[208:211], v[32:35]
	v_mfma_f32_16x16x32_bf16 v[28:31], v[140:143], v[208:211], v[28:31]
	v_mfma_f32_16x16x32_bf16 v[16:19], v[132:135], v[216:219], v[16:19]
	v_mfma_f32_16x16x32_bf16 v[12:15], v[140:143], v[216:219], v[12:15]
	v_mfma_f32_16x16x32_bf16 v[64:67], v[136:139], v[182:185], v[64:67]
	v_mfma_f32_16x16x32_bf16 v[60:63], v[144:147], v[182:185], v[60:63]
	v_mfma_f32_16x16x32_bf16 v[48:51], v[136:139], v[190:193], v[48:51]
	v_mfma_f32_16x16x32_bf16 v[44:47], v[144:147], v[190:193], v[44:47]
	v_mfma_f32_16x16x32_bf16 v[32:35], v[136:139], v[212:215], v[32:35]
	v_mfma_f32_16x16x32_bf16 v[28:31], v[144:147], v[212:215], v[28:31]
	v_mfma_f32_16x16x32_bf16 v[16:19], v[136:139], v[220:223], v[16:19]
	v_mfma_f32_16x16x32_bf16 v[12:15], v[144:147], v[220:223], v[12:15]
	s_setprio 0
	s_setprio 1
	v_mfma_f32_16x16x32_bf16 v[56:59], v[148:151], v[164:167], v[56:59]
	v_mfma_f32_16x16x32_bf16 v[52:55], v[156:159], v[164:167], v[52:55]
	v_mfma_f32_16x16x32_bf16 v[40:43], v[148:151], v[186:189], v[40:43]
	v_mfma_f32_16x16x32_bf16 v[36:39], v[156:159], v[186:189], v[36:39]
	v_mfma_f32_16x16x32_bf16 v[24:27], v[148:151], v[208:211], v[24:27]
	v_mfma_f32_16x16x32_bf16 v[20:23], v[156:159], v[208:211], v[20:23]
	v_mfma_f32_16x16x32_bf16 v[8:11], v[148:151], v[216:219], v[8:11]
	v_mfma_f32_16x16x32_bf16 v[4:7], v[156:159], v[216:219], v[4:7]
	v_mfma_f32_16x16x32_bf16 v[56:59], v[152:155], v[182:185], v[56:59]
	v_mfma_f32_16x16x32_bf16 v[52:55], v[160:163], v[182:185], v[52:55]
	v_mfma_f32_16x16x32_bf16 v[40:43], v[152:155], v[190:193], v[40:43]
	v_mfma_f32_16x16x32_bf16 v[36:39], v[160:163], v[190:193], v[36:39]
	v_mfma_f32_16x16x32_bf16 v[24:27], v[152:155], v[212:215], v[24:27]
	v_mfma_f32_16x16x32_bf16 v[20:23], v[160:163], v[212:215], v[20:23]
	v_mfma_f32_16x16x32_bf16 v[8:11], v[152:155], v[220:223], v[8:11]
	v_mfma_f32_16x16x32_bf16 v[4:7], v[160:163], v[220:223], v[4:7]
	s_setprio 0
	s_barrier
	s_add_i32 s45, s45, 2
	s_add_u32 s8, s8, 0x100
	s_addc_u32 s9, s9, 0
	s_add_u32 s23, s23, 0x100
	s_addc_u32 s44, s44, 0
	s_cmp_gt_u32 s45, 13
	s_cbranch_scc0 .LBB0_100
	s_and_b64 vcc, exec, s[14:15]
	s_cbranch_vccz .LBB0_103
	s_barrier

; #define PG8_STAGE(bufoff, gbase, voff) do { _Pragma("unroll") for (int _i = 0; _i < 2; ++_i) \
;         __builtin_amdgcn_global_load_lds((const unsigned*)((const char*)(gbase) + (voff)[_i]), (PG8_LAS unsigned*)(lds + (bufoff) + ldsw + _i * 8192), 16, 0, 0); } while (0)
; #define PG8_LDA(dst, b, h) do { _Pragma("unroll") for (int m = 0; m < 4; ++m) _Pragma("unroll") for (int k = 0; k < 2; ++k) dst[m][k] = *(const PG8_LAS bf16x8*)(lds + PG8_SA(b, h) + aoff + m * 2048 + k * 1024); } while (0)
; #define PG8_LDB(dst, b, h) do { _Pragma("unroll") for (int n = 0; n < 2; ++n) _Pragma("unroll") for (int k = 0; k < 2; ++k) dst[n][k] = *(const PG8_LAS bf16x8*)(lds + PG8_SB(b, h) + boff + n * 2048 + k * 1024); } while (0)
; #define PG8_MMA(ai, bj, At, Bt) do { __builtin_amdgcn_s_setprio(1); _Pragma("unroll") for (int m = 0; m < 4; ++m) _Pragma("unroll") for (int n = 0; n < 2; ++n) _Pragma("unroll") for (int k = 0; k < 2; ++k) \
;         acc[ai][bj][m][n] = __builtin_amdgcn_mfma_f32_16x16x32_bf16(Bt[n][k], At[m][k], acc[ai][bj][m][n], 0, 0, 0); __builtin_amdgcn_s_setprio(0); } while (0)
; #define PG8_WAIT_V(n) asm volatile("s_waitcnt vmcnt(" #n ")" ::: "memory")
; #define PG8_BAR __builtin_amdgcn_s_barrier()
; template <class Epi, class Sched, bool ALIGN_EPI = false, bool SP2 = false>
; __device__ __forceinline__ void gemm_phase(PG8_LAS unsigned char* lds, const Gemm g, const Sched& S, const Epi& E) {
;     ...
;         for (int t = 0; t < nt; t += 2) {
;             const bool last = (t == nt - 2);
;             const char* a1 = cA + (size_t)(t + 1) * kstep;
;             const char* a2 = last ? nA : cA + (size_t)(t + 2) * kstep; const char* b2 = last ? nB : cB + (size_t)(t + 2) * kstep;
;             const char* a3 = a2 + kstep; const char* b3 = b2 + kstep;
;             if (last && has_next) S.a_ready(nxt);
;             if constexpr (SP2) {
;             PG8_LDB(B0, 0, 0); PG8_LDB(B1, 0, 1); PG8_SCHED; PG8_LDA(At, 0, 0); PG8_STAGE(PG8_SA(1, 1), a1 + hstep, voffA);
;             PG8_WAIT_V(8); PG8_WAIT_L(0); PG8_BAR; PG8_MMA(0, 0, At, B0); PG8_MMA(0, 1, At, B1); PG8_BAR; PG8_SCHED;
;             PG8_LDA(At, 0, 1); PG8_STAGE(PG8_SB(0, 0), b2, voffB); PG8_STAGE(PG8_SB(0, 1), b2 + hstep, voffB); PG8_STAGE(PG8_SA(0, 0), a2, voffA);
;             PG8_WAIT_V(8); PG8_WAIT_L(0); PG8_BAR; PG8_MMA(1, 0, At, B0); PG8_MMA(1, 1, At, B1); PG8_BAR; PG8_SCHED;
.LBB0_329:
	s_add_u32 s30, s28, 0xfffc0080
	s_addc_u32 s31, s29, -1
	s_add_i32 s52, 0, 0x10000
	s_cmp_eq_u32 s45, 12
	s_cselect_b32 s35, s3, s31
	s_cselect_b32 s34, s17, s30
	s_cselect_b32 s31, s19, s44
	s_cselect_b32 s30, s25, s27
	s_add_i32 s54, 0, 0x14000
	v_add_u32_e32 v128, s52, v251
	v_add_u32_e32 v156, s54, v251
	ds_read_b128 v[108:111], v128
	ds_read_b128 v[112:115], v128 offset:1024
	ds_read_b128 v[124:127], v128 offset:2048
	ds_read_b128 v[128:131], v128 offset:3072
	ds_read_b128 v[132:135], v156
	ds_read_b128 v[140:143], v156 offset:1024
	ds_read_b128 v[148:151], v156 offset:2048
	ds_read_b128 v[156:159], v156 offset:3072
	v_lshl_add_u64 v[212:213], s[28:29], 0, v[208:209]
	s_add_i32 m0, s42, 0xc000
	ds_read_b128 v[164:167], v253
	ds_read_b128 v[168:171], v253 offset:1024
	ds_read_b128 v[172:175], v253 offset:2048
	ds_read_b128 v[176:179], v253 offset:3072
	ds_read_b128 v[180:183], v253 offset:4096
	ds_read_b128 v[184:187], v253 offset:5120
	ds_read_b128 v[188:191], v253 offset:6144
	ds_read_b128 v[192:195], v253 offset:7168
	global_load_lds_dwordx4 v[212:213], off
	s_add_i32 m0, s42, 0xe000
	v_lshl_add_u64 v[212:213], s[28:29], 0, v[210:211]
	global_load_lds_dwordx4 v[212:213], off
	s_waitcnt vmcnt(8) lgkmcnt(0)
	s_barrier
	s_setprio 1
	v_mfma_f32_16x16x32_bf16 v[160:163], v[108:111], v[164:167], v[160:163]
	v_mfma_f32_16x16x32_bf16 v[152:155], v[124:127], v[164:167], v[152:155]
	v_mfma_f32_16x16x32_bf16 v[120:123], v[108:111], v[172:175], v[120:123]
	v_mfma_f32_16x16x32_bf16 v[116:119], v[124:127], v[172:175], v[116:119]
	v_mfma_f32_16x16x32_bf16 v[96:99], v[108:111], v[180:183], v[96:99]
	v_mfma_f32_16x16x32_bf16 v[92:95], v[124:127], v[180:183], v[92:95]
	v_mfma_f32_16x16x32_bf16 v[80:83], v[108:111], v[188:191], v[80:83]
	v_mfma_f32_16x16x32_bf16 v[76:79], v[124:127], v[188:191], v[76:79]
	v_mfma_f32_16x16x32_bf16 v[160:163], v[112:115], v[168:171], v[160:163]
	v_mfma_f32_16x16x32_bf16 v[152:155], v[128:131], v[168:171], v[152:155]
	v_mfma_f32_16x16x32_bf16 v[120:123], v[112:115], v[176:179], v[120:123]
	v_mfma_f32_16x16x32_bf16 v[116:119], v[128:131], v[176:179], v[116:119]
	v_mfma_f32_16x16x32_bf16 v[96:99], v[112:115], v[184:187], v[96:99]
	v_mfma_f32_16x16x32_bf16 v[92:95], v[128:131], v[184:187], v[92:95]
	v_mfma_f32_16x16x32_bf16 v[80:83], v[112:115], v[192:195], v[80:83]
	v_mfma_f32_16x16x32_bf16 v[76:79], v[128:131], v[192:195], v[76:79]
	s_setprio 0
	s_setprio 1
	v_mfma_f32_16x16x32_bf16 v[144:147], v[132:135], v[164:167], v[144:147]
	v_mfma_f32_16x16x32_bf16 v[136:139], v[148:151], v[164:167], v[136:139]
	v_mfma_f32_16x16x32_bf16 v[104:107], v[132:135], v[172:175], v[104:107]
	v_mfma_f32_16x16x32_bf16 v[100:103], v[148:151], v[172:175], v[100:103]
	v_mfma_f32_16x16x32_bf16 v[88:91], v[132:135], v[180:183], v[88:91]
	v_mfma_f32_16x16x32_bf16 v[84:87], v[148:151], v[180:183], v[84:87]
	v_mfma_f32_16x16x32_bf16 v[72:75], v[132:135], v[188:191], v[72:75]
	v_mfma_f32_16x16x32_bf16 v[68:71], v[148:151], v[188:191], v[68:71]
	v_mfma_f32_16x16x32_bf16 v[144:147], v[140:143], v[168:171], v[144:147]
	v_mfma_f32_16x16x32_bf16 v[136:139], v[156:159], v[168:171], v[136:139]
	v_mfma_f32_16x16x32_bf16 v[104:107], v[140:143], v[176:179], v[104:107]
	v_mfma_f32_16x16x32_bf16 v[100:103], v[156:159], v[176:179], v[100:103]
	v_mfma_f32_16x16x32_bf16 v[88:91], v[140:143], v[184:187], v[88:91]
	v_mfma_f32_16x16x32_bf16 v[84:87], v[156:159], v[184:187], v[84:87]
	v_mfma_f32_16x16x32_bf16 v[72:75], v[140:143], v[192:195], v[72:75]
	v_mfma_f32_16x16x32_bf16 v[68:71], v[156:159], v[192:195], v[68:71]
	s_setprio 0
	s_barrier
	s_add_i32 s52, s52, s41
	v_lshl_add_u64 v[212:213], s[30:31], 0, v[202:203]
	s_mov_b32 m0, s52
	ds_read_b128 v[164:167], v253 offset:16384
	ds_read_b128 v[168:171], v253 offset:17408
	ds_read_b128 v[172:175], v253 offset:18432
	ds_read_b128 v[176:179], v253 offset:19456
	ds_read_b128 v[180:183], v253 offset:20480
	ds_read_b128 v[184:187], v253 offset:21504
	ds_read_b128 v[188:191], v253 offset:22528
	ds_read_b128 v[192:195], v253 offset:23552
	global_load_lds_dwordx4 v[212:213], off
	s_add_i32 m0, s52, 0x2000
	s_add_u32 s52, s30, 0x40000
	v_lshl_add_u64 v[214:215], s[30:31], 0, v[206:207]
	s_addc_u32 s53, s31, 0
	s_add_i32 s54, s54, s41
	global_load_lds_dwordx4 v[214:215], off
	v_lshl_add_u64 v[216:217], s[52:53], 0, v[202:203]
	s_mov_b32 m0, s54
	v_lshl_add_u64 v[218:219], s[34:35], 0, v[204:205]
	global_load_lds_dwordx4 v[216:217], off
	s_add_i32 m0, s54, 0x2000
	v_lshl_add_u64 v[216:217], s[52:53], 0, v[206:207]
	global_load_lds_dwordx4 v[216:217], off
	s_mov_b32 m0, s42
	v_lshl_add_u64 v[216:217], s[34:35], 0, v[0:1]
	global_load_lds_dwordx4 v[216:217], off
	s_mov_b32 m0, s43
	s_nop 0
	global_load_lds_dwordx4 v[218:219], off
	s_waitcnt vmcnt(8) lgkmcnt(0)
	s_barrier
; #define PG8_STAGE(bufoff, gbase, voff) do { _Pragma("unroll") for (int _i = 0; _i < 2; ++_i) \
;         __builtin_amdgcn_global_load_lds((const unsigned*)((const char*)(gbase) + (voff)[_i]), (PG8_LAS unsigned*)(lds + (bufoff) + ldsw + _i * 8192), 16, 0, 0); } while (0)
; #define PG8_LDA(dst, b, h) do { _Pragma("unroll") for (int m = 0; m < 4; ++m) _Pragma("unroll") for (int k = 0; k < 2; ++k) dst[m][k] = *(const PG8_LAS bf16x8*)(lds + PG8_SA(b, h) + aoff + m * 2048 + k * 1024); } while (0)
; #define PG8_LDB(dst, b, h) do { _Pragma("unroll") for (int n = 0; n < 2; ++n) _Pragma("unroll") for (int k = 0; k < 2; ++k) dst[n][k] = *(const PG8_LAS bf16x8*)(lds + PG8_SB(b, h) + boff + n * 2048 + k * 1024); } while (0)
; #define PG8_MMA(ai, bj, At, Bt) do { __builtin_amdgcn_s_setprio(1); _Pragma("unroll") for (int m = 0; m < 4; ++m) _Pragma("unroll") for (int n = 0; n < 2; ++n) _Pragma("unroll") for (int k = 0; k < 2; ++k) \
;         acc[ai][bj][m][n] = __builtin_amdgcn_mfma_f32_16x16x32_bf16(Bt[n][k], At[m][k], acc[ai][bj][m][n], 0, 0, 0); __builtin_amdgcn_s_setprio(0); } while (0)
; #define PG8_WAIT_V(n) asm volatile("s_waitcnt vmcnt(" #n ")" ::: "memory")
; #define PG8_WAIT_L(n) asm volatile("s_waitcnt lgkmcnt(" #n ")" ::: "memory")
; #define PG8_BAR __builtin_amdgcn_s_barrier()
; #define PG8_SCHED __builtin_amdgcn_sched_barrier(0)
; template <class Epi, class Sched, bool ALIGN_EPI = false, bool SP2 = false>
; __device__ __forceinline__ void gemm_phase(PG8_LAS unsigned char* lds, const Gemm g, const Sched& S, const Epi& E) {
;     ...
;             PG8_WAIT_V(8); PG8_WAIT_L(0); PG8_BAR; PG8_MMA(1, 0, At, B0); PG8_MMA(1, 1, At, B1); PG8_BAR; PG8_SCHED;
;             PG8_LDB(B0, 1, 0); PG8_LDB(B1, 1, 1); PG8_SCHED; PG8_LDA(At, 1, 0); PG8_STAGE(PG8_SA(0, 1), a2 + hstep, voffA);
;             PG8_WAIT_V(8); PG8_WAIT_L(0); PG8_BAR; PG8_MMA(0, 0, At, B0); PG8_MMA(0, 1, At, B1); PG8_BAR; PG8_SCHED;
	s_setprio 1
	v_mfma_f32_16x16x32_bf16 v[64:67], v[108:111], v[164:167], v[64:67]
	v_mfma_f32_16x16x32_bf16 v[60:63], v[124:127], v[164:167], v[60:63]
	v_mfma_f32_16x16x32_bf16 v[48:51], v[108:111], v[172:175], v[48:51]
	v_mfma_f32_16x16x32_bf16 v[44:47], v[124:127], v[172:175], v[44:47]
	v_mfma_f32_16x16x32_bf16 v[32:35], v[108:111], v[180:183], v[32:35]
	v_mfma_f32_16x16x32_bf16 v[28:31], v[124:127], v[180:183], v[28:31]
	v_mfma_f32_16x16x32_bf16 v[16:19], v[108:111], v[188:191], v[16:19]
	v_mfma_f32_16x16x32_bf16 v[12:15], v[124:127], v[188:191], v[12:15]
	v_mfma_f32_16x16x32_bf16 v[64:67], v[112:115], v[168:171], v[64:67]
	v_mfma_f32_16x16x32_bf16 v[60:63], v[128:131], v[168:171], v[60:63]
	v_mfma_f32_16x16x32_bf16 v[48:51], v[112:115], v[176:179], v[48:51]
	v_mfma_f32_16x16x32_bf16 v[44:47], v[128:131], v[176:179], v[44:47]
	v_mfma_f32_16x16x32_bf16 v[32:35], v[112:115], v[184:187], v[32:35]
	v_mfma_f32_16x16x32_bf16 v[28:31], v[128:131], v[184:187], v[28:31]
	v_mfma_f32_16x16x32_bf16 v[16:19], v[112:115], v[192:195], v[16:19]
	v_mfma_f32_16x16x32_bf16 v[12:15], v[128:131], v[192:195], v[12:15]
	s_setprio 0
	s_setprio 1
	v_mfma_f32_16x16x32_bf16 v[56:59], v[132:135], v[164:167], v[56:59]
	v_mfma_f32_16x16x32_bf16 v[52:55], v[148:151], v[164:167], v[52:55]
	v_mfma_f32_16x16x32_bf16 v[40:43], v[132:135], v[172:175], v[40:43]
	v_mfma_f32_16x16x32_bf16 v[36:39], v[148:151], v[172:175], v[36:39]
	v_mfma_f32_16x16x32_bf16 v[24:27], v[132:135], v[180:183], v[24:27]
	v_mfma_f32_16x16x32_bf16 v[20:23], v[148:151], v[180:183], v[20:23]
	v_mfma_f32_16x16x32_bf16 v[8:11], v[132:135], v[188:191], v[8:11]
	v_mfma_f32_16x16x32_bf16 v[4:7], v[148:151], v[188:191], v[4:7]
	v_mfma_f32_16x16x32_bf16 v[56:59], v[140:143], v[168:171], v[56:59]
	v_mfma_f32_16x16x32_bf16 v[52:55], v[156:159], v[168:171], v[52:55]
	v_mfma_f32_16x16x32_bf16 v[40:43], v[140:143], v[176:179], v[40:43]
	v_mfma_f32_16x16x32_bf16 v[36:39], v[156:159], v[176:179], v[36:39]
	v_mfma_f32_16x16x32_bf16 v[24:27], v[140:143], v[184:187], v[24:27]
	v_mfma_f32_16x16x32_bf16 v[20:23], v[156:159], v[184:187], v[20:23]
	v_mfma_f32_16x16x32_bf16 v[8:11], v[140:143], v[192:195], v[8:11]
	v_mfma_f32_16x16x32_bf16 v[4:7], v[156:159], v[192:195], v[4:7]
	s_setprio 0
	s_barrier
	s_add_i32 s52, 0, 0x18000
	s_add_i32 s53, 0, 0x1c000
	v_add_u32_e32 v128, s52, v251
	v_add_u32_e32 v156, s53, v251
	ds_read_b128 v[108:111], v128
	ds_read_b128 v[112:115], v128 offset:1024
	ds_read_b128 v[124:127], v128 offset:2048
	ds_read_b128 v[128:131], v128 offset:3072
	ds_read_b128 v[132:135], v156
	ds_read_b128 v[140:143], v156 offset:1024
	ds_read_b128 v[148:151], v156 offset:2048
	ds_read_b128 v[156:159], v156 offset:3072
	s_add_u32 s34, s34, 0x40000
	s_addc_u32 s35, s35, 0
	s_mov_b32 m0, s46
	v_lshl_add_u64 v[220:221], s[34:35], 0, v[0:1]
	ds_read_b128 v[164:167], v253 offset:32768
	ds_read_b128 v[168:171], v253 offset:33792
	ds_read_b128 v[172:175], v253 offset:34816
	ds_read_b128 v[176:179], v253 offset:35840
	ds_read_b128 v[180:183], v253 offset:36864
	ds_read_b128 v[184:187], v253 offset:37888
	ds_read_b128 v[188:191], v253 offset:38912
	ds_read_b128 v[192:195], v253 offset:39936
	global_load_lds_dwordx4 v[220:221], off
	s_mov_b32 m0, s47
	v_lshl_add_u64 v[220:221], s[34:35], 0, v[204:205]
	global_load_lds_dwordx4 v[220:221], off
	s_waitcnt vmcnt(8) lgkmcnt(0)
	s_barrier
	s_setprio 1
	v_mfma_f32_16x16x32_bf16 v[160:163], v[108:111], v[164:167], v[160:163]
	v_mfma_f32_16x16x32_bf16 v[152:155], v[124:127], v[164:167], v[152:155]
	v_mfma_f32_16x16x32_bf16 v[120:123], v[108:111], v[172:175], v[120:123]
	v_mfma_f32_16x16x32_bf16 v[116:119], v[124:127], v[172:175], v[116:119]
	v_mfma_f32_16x16x32_bf16 v[96:99], v[108:111], v[180:183], v[96:99]
	v_mfma_f32_16x16x32_bf16 v[92:95], v[124:127], v[180:183], v[92:95]
	v_mfma_f32_16x16x32_bf16 v[80:83], v[108:111], v[188:191], v[80:83]
	v_mfma_f32_16x16x32_bf16 v[76:79], v[124:127], v[188:191], v[76:79]
	v_mfma_f32_16x16x32_bf16 v[160:163], v[112:115], v[168:171], v[160:163]
	v_mfma_f32_16x16x32_bf16 v[152:155], v[128:131], v[168:171], v[152:155]
	v_mfma_f32_16x16x32_bf16 v[120:123], v[112:115], v[176:179], v[120:123]
	v_mfma_f32_16x16x32_bf16 v[116:119], v[128:131], v[176:179], v[116:119]
	v_mfma_f32_16x16x32_bf16 v[96:99], v[112:115], v[184:187], v[96:99]
	v_mfma_f32_16x16x32_bf16 v[92:95], v[128:131], v[184:187], v[92:95]
	v_mfma_f32_16x16x32_bf16 v[80:83], v[112:115], v[192:195], v[80:83]
	v_mfma_f32_16x16x32_bf16 v[76:79], v[128:131], v[192:195], v[76:79]
	s_setprio 0
	s_setprio 1
	v_mfma_f32_16x16x32_bf16 v[144:147], v[132:135], v[164:167], v[144:147]
	v_mfma_f32_16x16x32_bf16 v[136:139], v[148:151], v[164:167], v[136:139]
	v_mfma_f32_16x16x32_bf16 v[104:107], v[132:135], v[172:175], v[104:107]
	v_mfma_f32_16x16x32_bf16 v[100:103], v[148:151], v[172:175], v[100:103]
	v_mfma_f32_16x16x32_bf16 v[88:91], v[132:135], v[180:183], v[88:91]
	v_mfma_f32_16x16x32_bf16 v[84:87], v[148:151], v[180:183], v[84:87]
	v_mfma_f32_16x16x32_bf16 v[72:75], v[132:135], v[188:191], v[72:75]
	v_mfma_f32_16x16x32_bf16 v[68:71], v[148:151], v[188:191], v[68:71]
	v_mfma_f32_16x16x32_bf16 v[144:147], v[140:143], v[168:171], v[144:147]
	v_mfma_f32_16x16x32_bf16 v[136:139], v[156:159], v[168:171], v[136:139]
	v_mfma_f32_16x16x32_bf16 v[104:107], v[140:143], v[176:179], v[104:107]
	v_mfma_f32_16x16x32_bf16 v[100:103], v[156:159], v[176:179], v[100:103]
	v_mfma_f32_16x16x32_bf16 v[88:91], v[140:143], v[184:187], v[88:91]
	v_mfma_f32_16x16x32_bf16 v[84:87], v[156:159], v[184:187], v[84:87]
	v_mfma_f32_16x16x32_bf16 v[72:75], v[140:143], v[192:195], v[72:75]
	v_mfma_f32_16x16x32_bf16 v[68:71], v[156:159], v[192:195], v[68:71]
	s_setprio 0
	s_barrier
; #define PG8_STAGE(bufoff, gbase, voff) do { _Pragma("unroll") for (int _i = 0; _i < 2; ++_i) \
;         __builtin_amdgcn_global_load_lds((const unsigned*)((const char*)(gbase) + (voff)[_i]), (PG8_LAS unsigned*)(lds + (bufoff) + ldsw + _i * 8192), 16, 0, 0); } while (0)
; #define PG8_LDA(dst, b, h) do { _Pragma("unroll") for (int m = 0; m < 4; ++m) _Pragma("unroll") for (int k = 0; k < 2; ++k) dst[m][k] = *(const PG8_LAS bf16x8*)(lds + PG8_SA(b, h) + aoff + m * 2048 + k * 1024); } while (0)
; #define PG8_MMA(ai, bj, At, Bt) do { __builtin_amdgcn_s_setprio(1); _Pragma("unroll") for (int m = 0; m < 4; ++m) _Pragma("unroll") for (int n = 0; n < 2; ++n) _Pragma("unroll") for (int k = 0; k < 2; ++k) \
;         acc[ai][bj][m][n] = __builtin_amdgcn_mfma_f32_16x16x32_bf16(Bt[n][k], At[m][k], acc[ai][bj][m][n], 0, 0, 0); __builtin_amdgcn_s_setprio(0); } while (0)
; #define PG8_WAIT_V(n) asm volatile("s_waitcnt vmcnt(" #n ")" ::: "memory")
; #define PG8_WAIT_L(n) asm volatile("s_waitcnt lgkmcnt(" #n ")" ::: "memory")
; #define PG8_BAR __builtin_amdgcn_s_barrier()
; #define PG8_SCHED __builtin_amdgcn_sched_barrier(0)
; template <class Epi, class Sched, bool ALIGN_EPI = false, bool SP2 = false>
; __device__ __forceinline__ void gemm_phase(PG8_LAS unsigned char* lds, const Gemm g, const Sched& S, const Epi& E) {
;     ...
;             PG8_LDA(At, 1, 1); PG8_STAGE(PG8_SB(1, 0), b3, voffB); PG8_STAGE(PG8_SB(1, 1), b3 + hstep, voffB); PG8_STAGE(PG8_SA(1, 0), a3, voffA);
;             PG8_WAIT_V(8); PG8_WAIT_L(0); PG8_BAR; PG8_MMA(1, 0, At, B0); PG8_MMA(1, 1, At, B1); PG8_BAR; PG8_SCHED;
;     ...
;         if constexpr (ALIGN_EPI) { if (wr == 0) PG8_BAR; }
	s_add_i32 s34, s52, s41
	v_lshl_add_u64 v[212:213], v[212:213], 0, s[82:83]
	s_mov_b32 m0, s34
	ds_read_b128 v[164:167], v253 offset:49152
	ds_read_b128 v[168:171], v253 offset:50176
	ds_read_b128 v[172:175], v253 offset:51200
	ds_read_b128 v[176:179], v253 offset:52224
	ds_read_b128 v[180:183], v253 offset:53248
	ds_read_b128 v[184:187], v253 offset:54272
	ds_read_b128 v[188:191], v253 offset:55296
	ds_read_b128 v[192:195], v253 offset:56320
	global_load_lds_dwordx4 v[212:213], off
	s_add_i32 m0, s34, 0x2000
	s_add_u32 s30, s30, 0x40080
	v_lshl_add_u64 v[212:213], v[214:215], 0, s[82:83]
	s_addc_u32 s31, s31, 0
	s_add_i32 s34, s53, s41
	global_load_lds_dwordx4 v[212:213], off
	s_mov_b32 m0, s34
	v_lshl_add_u64 v[212:213], s[30:31], 0, v[202:203]
	global_load_lds_dwordx4 v[212:213], off
	s_add_i32 m0, s34, 0x2000
	v_lshl_add_u64 v[212:213], s[30:31], 0, v[206:207]
	global_load_lds_dwordx4 v[212:213], off
	s_mov_b32 m0, s49
	v_lshl_add_u64 v[212:213], v[216:217], 0, s[82:83]
	global_load_lds_dwordx4 v[212:213], off
	s_mov_b32 m0, s50
	v_lshl_add_u64 v[212:213], v[218:219], 0, s[82:83]
	global_load_lds_dwordx4 v[212:213], off
	s_waitcnt vmcnt(8) lgkmcnt(0)
	s_barrier
	s_setprio 1
	v_mfma_f32_16x16x32_bf16 v[64:67], v[108:111], v[164:167], v[64:67]
	v_mfma_f32_16x16x32_bf16 v[60:63], v[124:127], v[164:167], v[60:63]
	v_mfma_f32_16x16x32_bf16 v[48:51], v[108:111], v[172:175], v[48:51]
	v_mfma_f32_16x16x32_bf16 v[44:47], v[124:127], v[172:175], v[44:47]
	v_mfma_f32_16x16x32_bf16 v[32:35], v[108:111], v[180:183], v[32:35]
	v_mfma_f32_16x16x32_bf16 v[28:31], v[124:127], v[180:183], v[28:31]
	v_mfma_f32_16x16x32_bf16 v[16:19], v[108:111], v[188:191], v[16:19]
	v_mfma_f32_16x16x32_bf16 v[12:15], v[124:127], v[188:191], v[12:15]
	v_mfma_f32_16x16x32_bf16 v[64:67], v[112:115], v[168:171], v[64:67]
	v_mfma_f32_16x16x32_bf16 v[60:63], v[128:131], v[168:171], v[60:63]
	v_mfma_f32_16x16x32_bf16 v[48:51], v[112:115], v[176:179], v[48:51]
	v_mfma_f32_16x16x32_bf16 v[44:47], v[128:131], v[176:179], v[44:47]
	v_mfma_f32_16x16x32_bf16 v[32:35], v[112:115], v[184:187], v[32:35]
	v_mfma_f32_16x16x32_bf16 v[28:31], v[128:131], v[184:187], v[28:31]
	v_mfma_f32_16x16x32_bf16 v[16:19], v[112:115], v[192:195], v[16:19]
	v_mfma_f32_16x16x32_bf16 v[12:15], v[128:131], v[192:195], v[12:15]
	s_setprio 0
	s_setprio 1
	v_mfma_f32_16x16x32_bf16 v[56:59], v[132:135], v[164:167], v[56:59]
	v_mfma_f32_16x16x32_bf16 v[52:55], v[148:151], v[164:167], v[52:55]
	v_mfma_f32_16x16x32_bf16 v[40:43], v[132:135], v[172:175], v[40:43]
	v_mfma_f32_16x16x32_bf16 v[36:39], v[148:151], v[172:175], v[36:39]
	v_mfma_f32_16x16x32_bf16 v[24:27], v[132:135], v[180:183], v[24:27]
	v_mfma_f32_16x16x32_bf16 v[20:23], v[148:151], v[180:183], v[20:23]
	v_mfma_f32_16x16x32_bf16 v[8:11], v[132:135], v[188:191], v[8:11]
	v_mfma_f32_16x16x32_bf16 v[4:7], v[148:151], v[188:191], v[4:7]
	v_mfma_f32_16x16x32_bf16 v[56:59], v[140:143], v[168:171], v[56:59]
	v_mfma_f32_16x16x32_bf16 v[52:55], v[156:159], v[168:171], v[52:55]
	v_mfma_f32_16x16x32_bf16 v[40:43], v[140:143], v[176:179], v[40:43]
	v_mfma_f32_16x16x32_bf16 v[36:39], v[156:159], v[176:179], v[36:39]
	v_mfma_f32_16x16x32_bf16 v[24:27], v[140:143], v[184:187], v[24:27]
	v_mfma_f32_16x16x32_bf16 v[20:23], v[156:159], v[184:187], v[20:23]
	v_mfma_f32_16x16x32_bf16 v[8:11], v[140:143], v[192:195], v[8:11]
	v_mfma_f32_16x16x32_bf16 v[4:7], v[156:159], v[192:195], v[4:7]
	s_setprio 0
	s_barrier
	s_add_i32 s45, s45, 2
	s_add_u32 s28, s28, 0x100
	s_addc_u32 s29, s29, 0
	s_add_u32 s27, s27, 0x100
	s_addc_u32 s44, s44, 0
	s_cmp_gt_u32 s45, 13
	s_cbranch_scc0 .LBB0_329
	s_and_b64 vcc, exec, s[14:15]
	s_cbranch_vccz .LBB0_332
	s_barrier

; #define PG8_STAGE(bufoff, gbase, voff) do { _Pragma("unroll") for (int _i = 0; _i < 2; ++_i) \
;         __builtin_amdgcn_global_load_lds((const unsigned*)((const char*)(gbase) + (voff)[_i]), (PG8_LAS unsigned*)(lds + (bufoff) + ldsw + _i * 8192), 16, 0, 0); } while (0)
; #define PG8_LDA(dst, b, h) do { _Pragma("unroll") for (int m = 0; m < 4; ++m) _Pragma("unroll") for (int k = 0; k < 2; ++k) dst[m][k] = *(const PG8_LAS bf16x8*)(lds + PG8_SA(b, h) + aoff + m * 2048 + k * 1024); } while (0)
; #define PG8_LDB(dst, b, h) do { _Pragma("unroll") for (int n = 0; n < 2; ++n) _Pragma("unroll") for (int k = 0; k < 2; ++k) dst[n][k] = *(const PG8_LAS bf16x8*)(lds + PG8_SB(b, h) + boff + n * 2048 + k * 1024); } while (0)
; #define PG8_MMA(ai, bj, At, Bt) do { __builtin_amdgcn_s_setprio(1); _Pragma("unroll") for (int m = 0; m < 4; ++m) _Pragma("unroll") for (int n = 0; n < 2; ++n) _Pragma("unroll") for (int k = 0; k < 2; ++k) \
;         acc[ai][bj][m][n] = __builtin_amdgcn_mfma_f32_16x16x32_bf16(Bt[n][k], At[m][k], acc[ai][bj][m][n], 0, 0, 0); __builtin_amdgcn_s_setprio(0); } while (0)
; #define PG8_WAIT_V(n) asm volatile("s_waitcnt vmcnt(" #n ")" ::: "memory")
; #define PG8_BAR __builtin_amdgcn_s_barrier()
; template <class Epi, class Sched, bool ALIGN_EPI = false, bool SP2 = false>
; __device__ __forceinline__ void gemm_phase(PG8_LAS unsigned char* lds, const Gemm g, const Sched& S, const Epi& E) {
;     ...
;         for (int t = 0; t < nt; t += 2) {
;             const bool last = (t == nt - 2);
;             const char* a1 = cA + (size_t)(t + 1) * kstep;
;             const char* a2 = last ? nA : cA + (size_t)(t + 2) * kstep; const char* b2 = last ? nB : cB + (size_t)(t + 2) * kstep;
;             const char* a3 = a2 + kstep; const char* b3 = b2 + kstep;
;             if (last && has_next) S.a_ready(nxt);
;             if constexpr (SP2) {
;             PG8_LDB(B0, 0, 0); PG8_LDB(B1, 0, 1); PG8_SCHED; PG8_LDA(At, 0, 0); PG8_STAGE(PG8_SA(1, 1), a1 + hstep, voffA);
;             PG8_WAIT_V(8); PG8_WAIT_L(0); PG8_BAR; PG8_MMA(0, 0, At, B0); PG8_MMA(0, 1, At, B1); PG8_BAR; PG8_SCHED;
;             PG8_LDA(At, 0, 1); PG8_STAGE(PG8_SB(0, 0), b2, voffB); PG8_STAGE(PG8_SB(0, 1), b2 + hstep, voffB); PG8_STAGE(PG8_SA(0, 0), a2, voffA);
;             PG8_WAIT_V(8); PG8_WAIT_L(0); PG8_BAR; PG8_MMA(1, 0, At, B0); PG8_MMA(1, 1, At, B1); PG8_BAR; PG8_SCHED;
.LBB0_405:
	s_add_u32 s24, s8, 0xfffc0080
	s_addc_u32 s25, s9, -1
	s_add_i32 s47, 0, 0x10000
	s_cmp_eq_u32 s46, 12
	s_cselect_b32 s27, s7, s25
	s_cselect_b32 s26, s17, s24
	s_cselect_b32 s25, s19, s45
	s_cselect_b32 s24, s43, s44
	s_add_i32 s50, 0, 0x14000
	v_add_u32_e32 v156, s47, v164
	v_add_u32_e32 v167, s50, v164
	ds_read_b128 v[144:147], v156
	ds_read_b128 v[148:151], v156 offset:1024
	ds_read_b128 v[152:155], v156 offset:2048
	ds_read_b128 v[156:159], v156 offset:3072
	ds_read_b128 v[160:163], v167
	ds_read_b128 v[168:171], v167 offset:1024
	ds_read_b128 v[172:175], v167 offset:2048
	ds_read_b128 v[176:179], v167 offset:3072
	v_lshl_add_u64 v[198:199], s[8:9], 0, v[140:141]
	s_add_i32 m0, s37, 0xc000
	ds_read_b128 v[180:183], v166
	ds_read_b128 v[184:187], v166 offset:1024
	ds_read_b128 v[188:191], v166 offset:2048
	ds_read_b128 v[192:195], v166 offset:3072
	ds_read_b128 v[202:205], v166 offset:4096
	ds_read_b128 v[206:209], v166 offset:5120
	ds_read_b128 v[210:213], v166 offset:6144
	ds_read_b128 v[214:217], v166 offset:7168
	global_load_lds_dwordx4 v[198:199], off
	s_add_i32 m0, s37, 0xe000
	v_lshl_add_u64 v[198:199], s[8:9], 0, v[142:143]
	global_load_lds_dwordx4 v[198:199], off
	s_waitcnt vmcnt(8) lgkmcnt(0)
	s_barrier
	s_setprio 1
	v_mfma_f32_16x16x32_bf16 v[128:131], v[144:147], v[180:183], v[128:131]
	v_mfma_f32_16x16x32_bf16 v[120:123], v[152:155], v[180:183], v[120:123]
	v_mfma_f32_16x16x32_bf16 v[112:115], v[144:147], v[188:191], v[112:115]
	v_mfma_f32_16x16x32_bf16 v[104:107], v[152:155], v[188:191], v[104:107]
	v_mfma_f32_16x16x32_bf16 v[96:99], v[144:147], v[202:205], v[96:99]
	v_mfma_f32_16x16x32_bf16 v[88:91], v[152:155], v[202:205], v[88:91]
	v_mfma_f32_16x16x32_bf16 v[80:83], v[144:147], v[210:213], v[80:83]
	v_mfma_f32_16x16x32_bf16 v[72:75], v[152:155], v[210:213], v[72:75]
	v_mfma_f32_16x16x32_bf16 v[128:131], v[148:151], v[184:187], v[128:131]
	v_mfma_f32_16x16x32_bf16 v[120:123], v[156:159], v[184:187], v[120:123]
	v_mfma_f32_16x16x32_bf16 v[112:115], v[148:151], v[192:195], v[112:115]
	v_mfma_f32_16x16x32_bf16 v[104:107], v[156:159], v[192:195], v[104:107]
	v_mfma_f32_16x16x32_bf16 v[96:99], v[148:151], v[206:209], v[96:99]
	v_mfma_f32_16x16x32_bf16 v[88:91], v[156:159], v[206:209], v[88:91]
	v_mfma_f32_16x16x32_bf16 v[80:83], v[148:151], v[214:217], v[80:83]
	v_mfma_f32_16x16x32_bf16 v[72:75], v[156:159], v[214:217], v[72:75]
	s_setprio 0
	s_setprio 1
	v_mfma_f32_16x16x32_bf16 v[124:127], v[160:163], v[180:183], v[124:127]
	v_mfma_f32_16x16x32_bf16 v[116:119], v[172:175], v[180:183], v[116:119]
	v_mfma_f32_16x16x32_bf16 v[108:111], v[160:163], v[188:191], v[108:111]
	v_mfma_f32_16x16x32_bf16 v[100:103], v[172:175], v[188:191], v[100:103]
	v_mfma_f32_16x16x32_bf16 v[92:95], v[160:163], v[202:205], v[92:95]
	v_mfma_f32_16x16x32_bf16 v[84:87], v[172:175], v[202:205], v[84:87]
	v_mfma_f32_16x16x32_bf16 v[76:79], v[160:163], v[210:213], v[76:79]
	v_mfma_f32_16x16x32_bf16 v[68:71], v[172:175], v[210:213], v[68:71]
	v_mfma_f32_16x16x32_bf16 v[124:127], v[168:171], v[184:187], v[124:127]
	v_mfma_f32_16x16x32_bf16 v[116:119], v[176:179], v[184:187], v[116:119]
	v_mfma_f32_16x16x32_bf16 v[108:111], v[168:171], v[192:195], v[108:111]
	v_mfma_f32_16x16x32_bf16 v[100:103], v[176:179], v[192:195], v[100:103]
	v_mfma_f32_16x16x32_bf16 v[92:95], v[168:171], v[206:209], v[92:95]
	v_mfma_f32_16x16x32_bf16 v[84:87], v[176:179], v[206:209], v[84:87]
	v_mfma_f32_16x16x32_bf16 v[76:79], v[168:171], v[214:217], v[76:79]
	v_mfma_f32_16x16x32_bf16 v[68:71], v[176:179], v[214:217], v[68:71]
	s_setprio 0
	s_barrier
	s_add_i32 s47, s47, s35
	v_lshl_add_u64 v[198:199], s[24:25], 0, v[134:135]
	s_mov_b32 m0, s47
	ds_read_b128 v[180:183], v166 offset:16384
	ds_read_b128 v[184:187], v166 offset:17408
	ds_read_b128 v[188:191], v166 offset:18432
	ds_read_b128 v[192:195], v166 offset:19456
	ds_read_b128 v[202:205], v166 offset:20480
	ds_read_b128 v[206:209], v166 offset:21504
	ds_read_b128 v[210:213], v166 offset:22528
	ds_read_b128 v[214:217], v166 offset:23552
	global_load_lds_dwordx4 v[198:199], off
	s_add_i32 m0, s47, 0x2000
	s_add_u32 s48, s24, 0x40000
	v_lshl_add_u64 v[218:219], s[24:25], 0, v[0:1]
	s_addc_u32 s49, s25, 0
	s_add_i32 s47, s50, s35
	global_load_lds_dwordx4 v[218:219], off
	v_lshl_add_u64 v[220:221], s[48:49], 0, v[134:135]
	s_mov_b32 m0, s47
	v_lshl_add_u64 v[222:223], s[26:27], 0, v[132:133]
	global_load_lds_dwordx4 v[220:221], off
	s_add_i32 m0, s47, 0x2000
	v_lshl_add_u64 v[220:221], s[48:49], 0, v[0:1]
	global_load_lds_dwordx4 v[220:221], off
	s_mov_b32 m0, s37
	v_lshl_add_u64 v[220:221], s[26:27], 0, v[136:137]
	global_load_lds_dwordx4 v[220:221], off
	s_mov_b32 m0, s38
	s_nop 0
	global_load_lds_dwordx4 v[222:223], off
	s_waitcnt vmcnt(8) lgkmcnt(0)
	s_barrier
; #define PG8_STAGE(bufoff, gbase, voff) do { _Pragma("unroll") for (int _i = 0; _i < 2; ++_i) \
;         __builtin_amdgcn_global_load_lds((const unsigned*)((const char*)(gbase) + (voff)[_i]), (PG8_LAS unsigned*)(lds + (bufoff) + ldsw + _i * 8192), 16, 0, 0); } while (0)
; #define PG8_LDA(dst, b, h) do { _Pragma("unroll") for (int m = 0; m < 4; ++m) _Pragma("unroll") for (int k = 0; k < 2; ++k) dst[m][k] = *(const PG8_LAS bf16x8*)(lds + PG8_SA(b, h) + aoff + m * 2048 + k * 1024); } while (0)
; #define PG8_LDB(dst, b, h) do { _Pragma("unroll") for (int n = 0; n < 2; ++n) _Pragma("unroll") for (int k = 0; k < 2; ++k) dst[n][k] = *(const PG8_LAS bf16x8*)(lds + PG8_SB(b, h) + boff + n * 2048 + k * 1024); } while (0)
; #define PG8_MMA(ai, bj, At, Bt) do { __builtin_amdgcn_s_setprio(1); _Pragma("unroll") for (int m = 0; m < 4; ++m) _Pragma("unroll") for (int n = 0; n < 2; ++n) _Pragma("unroll") for (int k = 0; k < 2; ++k) \
;         acc[ai][bj][m][n] = __builtin_amdgcn_mfma_f32_16x16x32_bf16(Bt[n][k], At[m][k], acc[ai][bj][m][n], 0, 0, 0); __builtin_amdgcn_s_setprio(0); } while (0)
; #define PG8_WAIT_V(n) asm volatile("s_waitcnt vmcnt(" #n ")" ::: "memory")
; #define PG8_WAIT_L(n) asm volatile("s_waitcnt lgkmcnt(" #n ")" ::: "memory")
; #define PG8_BAR __builtin_amdgcn_s_barrier()
; #define PG8_SCHED __builtin_amdgcn_sched_barrier(0)
; template <class Epi, class Sched, bool ALIGN_EPI = false, bool SP2 = false>
; __device__ __forceinline__ void gemm_phase(PG8_LAS unsigned char* lds, const Gemm g, const Sched& S, const Epi& E) {
;     ...
;             PG8_WAIT_V(8); PG8_WAIT_L(0); PG8_BAR; PG8_MMA(1, 0, At, B0); PG8_MMA(1, 1, At, B1); PG8_BAR; PG8_SCHED;
;             PG8_LDB(B0, 1, 0); PG8_LDB(B1, 1, 1); PG8_SCHED; PG8_LDA(At, 1, 0); PG8_STAGE(PG8_SA(0, 1), a2 + hstep, voffA);
;             PG8_WAIT_V(8); PG8_WAIT_L(0); PG8_BAR; PG8_MMA(0, 0, At, B0); PG8_MMA(0, 1, At, B1); PG8_BAR; PG8_SCHED;
	s_setprio 1
	v_mfma_f32_16x16x32_bf16 v[64:67], v[144:147], v[180:183], v[64:67]
	v_mfma_f32_16x16x32_bf16 v[56:59], v[152:155], v[180:183], v[56:59]
	v_mfma_f32_16x16x32_bf16 v[48:51], v[144:147], v[188:191], v[48:51]
	v_mfma_f32_16x16x32_bf16 v[40:43], v[152:155], v[188:191], v[40:43]
	v_mfma_f32_16x16x32_bf16 v[32:35], v[144:147], v[202:205], v[32:35]
	v_mfma_f32_16x16x32_bf16 v[24:27], v[152:155], v[202:205], v[24:27]
	v_mfma_f32_16x16x32_bf16 v[16:19], v[144:147], v[210:213], v[16:19]
	v_mfma_f32_16x16x32_bf16 v[8:11], v[152:155], v[210:213], v[8:11]
	v_mfma_f32_16x16x32_bf16 v[64:67], v[148:151], v[184:187], v[64:67]
	v_mfma_f32_16x16x32_bf16 v[56:59], v[156:159], v[184:187], v[56:59]
	v_mfma_f32_16x16x32_bf16 v[48:51], v[148:151], v[192:195], v[48:51]
	v_mfma_f32_16x16x32_bf16 v[40:43], v[156:159], v[192:195], v[40:43]
	v_mfma_f32_16x16x32_bf16 v[32:35], v[148:151], v[206:209], v[32:35]
	v_mfma_f32_16x16x32_bf16 v[24:27], v[156:159], v[206:209], v[24:27]
	v_mfma_f32_16x16x32_bf16 v[16:19], v[148:151], v[214:217], v[16:19]
	v_mfma_f32_16x16x32_bf16 v[8:11], v[156:159], v[214:217], v[8:11]
	s_setprio 0
	s_setprio 1
	v_mfma_f32_16x16x32_bf16 v[60:63], v[160:163], v[180:183], v[60:63]
	v_mfma_f32_16x16x32_bf16 v[52:55], v[172:175], v[180:183], v[52:55]
	v_mfma_f32_16x16x32_bf16 v[44:47], v[160:163], v[188:191], v[44:47]
	v_mfma_f32_16x16x32_bf16 v[36:39], v[172:175], v[188:191], v[36:39]
	v_mfma_f32_16x16x32_bf16 v[28:31], v[160:163], v[202:205], v[28:31]
	v_mfma_f32_16x16x32_bf16 v[20:23], v[172:175], v[202:205], v[20:23]
	v_mfma_f32_16x16x32_bf16 v[12:15], v[160:163], v[210:213], v[12:15]
	v_mfma_f32_16x16x32_bf16 v[4:7], v[172:175], v[210:213], v[4:7]
	v_mfma_f32_16x16x32_bf16 v[60:63], v[168:171], v[184:187], v[60:63]
	v_mfma_f32_16x16x32_bf16 v[52:55], v[176:179], v[184:187], v[52:55]
	v_mfma_f32_16x16x32_bf16 v[44:47], v[168:171], v[192:195], v[44:47]
	v_mfma_f32_16x16x32_bf16 v[36:39], v[176:179], v[192:195], v[36:39]
	v_mfma_f32_16x16x32_bf16 v[28:31], v[168:171], v[206:209], v[28:31]
	v_mfma_f32_16x16x32_bf16 v[20:23], v[176:179], v[206:209], v[20:23]
	v_mfma_f32_16x16x32_bf16 v[12:15], v[168:171], v[214:217], v[12:15]
	v_mfma_f32_16x16x32_bf16 v[4:7], v[176:179], v[214:217], v[4:7]
	s_setprio 0
	s_barrier
	s_add_i32 s47, 0, 0x18000
	s_add_i32 s48, 0, 0x1c000
	v_add_u32_e32 v156, s47, v164
	v_add_u32_e32 v167, s48, v164
	ds_read_b128 v[144:147], v156
	ds_read_b128 v[148:151], v156 offset:1024
	ds_read_b128 v[152:155], v156 offset:2048
	ds_read_b128 v[156:159], v156 offset:3072
	ds_read_b128 v[160:163], v167
	ds_read_b128 v[168:171], v167 offset:1024
	ds_read_b128 v[172:175], v167 offset:2048
	ds_read_b128 v[176:179], v167 offset:3072
	s_add_u32 s26, s26, 0x40000
	s_addc_u32 s27, s27, 0
	s_mov_b32 m0, s39
	v_lshl_add_u64 v[224:225], s[26:27], 0, v[136:137]
	ds_read_b128 v[180:183], v166 offset:32768
	ds_read_b128 v[184:187], v166 offset:33792
	ds_read_b128 v[188:191], v166 offset:34816
	ds_read_b128 v[192:195], v166 offset:35840
	ds_read_b128 v[202:205], v166 offset:36864
	ds_read_b128 v[206:209], v166 offset:37888
	ds_read_b128 v[210:213], v166 offset:38912
	ds_read_b128 v[214:217], v166 offset:39936
	global_load_lds_dwordx4 v[224:225], off
	s_mov_b32 m0, s40
	v_lshl_add_u64 v[224:225], s[26:27], 0, v[132:133]
	global_load_lds_dwordx4 v[224:225], off
	s_waitcnt vmcnt(8) lgkmcnt(0)
	s_barrier
	s_setprio 1
	v_mfma_f32_16x16x32_bf16 v[128:131], v[144:147], v[180:183], v[128:131]
	v_mfma_f32_16x16x32_bf16 v[120:123], v[152:155], v[180:183], v[120:123]
	v_mfma_f32_16x16x32_bf16 v[112:115], v[144:147], v[188:191], v[112:115]
	v_mfma_f32_16x16x32_bf16 v[104:107], v[152:155], v[188:191], v[104:107]
	v_mfma_f32_16x16x32_bf16 v[96:99], v[144:147], v[202:205], v[96:99]
	v_mfma_f32_16x16x32_bf16 v[88:91], v[152:155], v[202:205], v[88:91]
	v_mfma_f32_16x16x32_bf16 v[80:83], v[144:147], v[210:213], v[80:83]
	v_mfma_f32_16x16x32_bf16 v[72:75], v[152:155], v[210:213], v[72:75]
	v_mfma_f32_16x16x32_bf16 v[128:131], v[148:151], v[184:187], v[128:131]
	v_mfma_f32_16x16x32_bf16 v[120:123], v[156:159], v[184:187], v[120:123]
	v_mfma_f32_16x16x32_bf16 v[112:115], v[148:151], v[192:195], v[112:115]
	v_mfma_f32_16x16x32_bf16 v[104:107], v[156:159], v[192:195], v[104:107]
	v_mfma_f32_16x16x32_bf16 v[96:99], v[148:151], v[206:209], v[96:99]
	v_mfma_f32_16x16x32_bf16 v[88:91], v[156:159], v[206:209], v[88:91]
	v_mfma_f32_16x16x32_bf16 v[80:83], v[148:151], v[214:217], v[80:83]
	v_mfma_f32_16x16x32_bf16 v[72:75], v[156:159], v[214:217], v[72:75]
	s_setprio 0
	s_setprio 1
	v_mfma_f32_16x16x32_bf16 v[124:127], v[160:163], v[180:183], v[124:127]
	v_mfma_f32_16x16x32_bf16 v[116:119], v[172:175], v[180:183], v[116:119]
	v_mfma_f32_16x16x32_bf16 v[108:111], v[160:163], v[188:191], v[108:111]
	v_mfma_f32_16x16x32_bf16 v[100:103], v[172:175], v[188:191], v[100:103]
	v_mfma_f32_16x16x32_bf16 v[92:95], v[160:163], v[202:205], v[92:95]
	v_mfma_f32_16x16x32_bf16 v[84:87], v[172:175], v[202:205], v[84:87]
	v_mfma_f32_16x16x32_bf16 v[76:79], v[160:163], v[210:213], v[76:79]
	v_mfma_f32_16x16x32_bf16 v[68:71], v[172:175], v[210:213], v[68:71]
	v_mfma_f32_16x16x32_bf16 v[124:127], v[168:171], v[184:187], v[124:127]
	v_mfma_f32_16x16x32_bf16 v[116:119], v[176:179], v[184:187], v[116:119]
	v_mfma_f32_16x16x32_bf16 v[108:111], v[168:171], v[192:195], v[108:111]
	v_mfma_f32_16x16x32_bf16 v[100:103], v[176:179], v[192:195], v[100:103]
	v_mfma_f32_16x16x32_bf16 v[92:95], v[168:171], v[206:209], v[92:95]
	v_mfma_f32_16x16x32_bf16 v[84:87], v[176:179], v[206:209], v[84:87]
	v_mfma_f32_16x16x32_bf16 v[76:79], v[168:171], v[214:217], v[76:79]
	v_mfma_f32_16x16x32_bf16 v[68:71], v[176:179], v[214:217], v[68:71]
	s_setprio 0
	s_barrier
; #define PG8_STAGE(bufoff, gbase, voff) do { _Pragma("unroll") for (int _i = 0; _i < 2; ++_i) \
;         __builtin_amdgcn_global_load_lds((const unsigned*)((const char*)(gbase) + (voff)[_i]), (PG8_LAS unsigned*)(lds + (bufoff) + ldsw + _i * 8192), 16, 0, 0); } while (0)
; #define PG8_LDA(dst, b, h) do { _Pragma("unroll") for (int m = 0; m < 4; ++m) _Pragma("unroll") for (int k = 0; k < 2; ++k) dst[m][k] = *(const PG8_LAS bf16x8*)(lds + PG8_SA(b, h) + aoff + m * 2048 + k * 1024); } while (0)
; #define PG8_MMA(ai, bj, At, Bt) do { __builtin_amdgcn_s_setprio(1); _Pragma("unroll") for (int m = 0; m < 4; ++m) _Pragma("unroll") for (int n = 0; n < 2; ++n) _Pragma("unroll") for (int k = 0; k < 2; ++k) \
;         acc[ai][bj][m][n] = __builtin_amdgcn_mfma_f32_16x16x32_bf16(Bt[n][k], At[m][k], acc[ai][bj][m][n], 0, 0, 0); __builtin_amdgcn_s_setprio(0); } while (0)
; #define PG8_WAIT_V(n) asm volatile("s_waitcnt vmcnt(" #n ")" ::: "memory")
; #define PG8_WAIT_L(n) asm volatile("s_waitcnt lgkmcnt(" #n ")" ::: "memory")
; #define PG8_BAR __builtin_amdgcn_s_barrier()
; #define PG8_SCHED __builtin_amdgcn_sched_barrier(0)
; template <class Epi, class Sched, bool ALIGN_EPI = false, bool SP2 = false>
; __device__ __forceinline__ void gemm_phase(PG8_LAS unsigned char* lds, const Gemm g, const Sched& S, const Epi& E) {
;     ...
;             PG8_LDA(At, 1, 1); PG8_STAGE(PG8_SB(1, 0), b3, voffB); PG8_STAGE(PG8_SB(1, 1), b3 + hstep, voffB); PG8_STAGE(PG8_SA(1, 0), a3, voffA);
;             PG8_WAIT_V(8); PG8_WAIT_L(0); PG8_BAR; PG8_MMA(1, 0, At, B0); PG8_MMA(1, 1, At, B1); PG8_BAR; PG8_SCHED;
;     ...
;         if constexpr (ALIGN_EPI) { if (wr == 0) PG8_BAR; }
	s_add_i32 s26, s47, s35
	v_lshl_add_u64 v[198:199], v[198:199], 0, s[82:83]
	s_mov_b32 m0, s26
	ds_read_b128 v[180:183], v166 offset:49152
	ds_read_b128 v[184:187], v166 offset:50176
	ds_read_b128 v[188:191], v166 offset:51200
	ds_read_b128 v[192:195], v166 offset:52224
	ds_read_b128 v[202:205], v166 offset:53248
	ds_read_b128 v[206:209], v166 offset:54272
	ds_read_b128 v[210:213], v166 offset:55296
	ds_read_b128 v[214:217], v166 offset:56320
	global_load_lds_dwordx4 v[198:199], off
	s_add_i32 m0, s26, 0x2000
	s_add_u32 s24, s24, 0x40080
	v_lshl_add_u64 v[198:199], v[218:219], 0, s[82:83]
	s_addc_u32 s25, s25, 0
	s_add_i32 s26, s48, s35
	global_load_lds_dwordx4 v[198:199], off
	s_mov_b32 m0, s26
	v_lshl_add_u64 v[198:199], s[24:25], 0, v[134:135]
	global_load_lds_dwordx4 v[198:199], off
	s_add_i32 m0, s26, 0x2000
	v_lshl_add_u64 v[198:199], s[24:25], 0, v[0:1]
	global_load_lds_dwordx4 v[198:199], off
	s_mov_b32 m0, s41
	v_lshl_add_u64 v[198:199], v[220:221], 0, s[82:83]
	global_load_lds_dwordx4 v[198:199], off
	s_mov_b32 m0, s42
	v_lshl_add_u64 v[198:199], v[222:223], 0, s[82:83]
	global_load_lds_dwordx4 v[198:199], off
	s_waitcnt vmcnt(8) lgkmcnt(0)
	s_barrier
	s_setprio 1
	v_mfma_f32_16x16x32_bf16 v[64:67], v[144:147], v[180:183], v[64:67]
	v_mfma_f32_16x16x32_bf16 v[56:59], v[152:155], v[180:183], v[56:59]
	v_mfma_f32_16x16x32_bf16 v[48:51], v[144:147], v[188:191], v[48:51]
	v_mfma_f32_16x16x32_bf16 v[40:43], v[152:155], v[188:191], v[40:43]
	v_mfma_f32_16x16x32_bf16 v[32:35], v[144:147], v[202:205], v[32:35]
	v_mfma_f32_16x16x32_bf16 v[24:27], v[152:155], v[202:205], v[24:27]
	v_mfma_f32_16x16x32_bf16 v[16:19], v[144:147], v[210:213], v[16:19]
	v_mfma_f32_16x16x32_bf16 v[8:11], v[152:155], v[210:213], v[8:11]
	v_mfma_f32_16x16x32_bf16 v[64:67], v[148:151], v[184:187], v[64:67]
	v_mfma_f32_16x16x32_bf16 v[56:59], v[156:159], v[184:187], v[56:59]
	v_mfma_f32_16x16x32_bf16 v[48:51], v[148:151], v[192:195], v[48:51]
	v_mfma_f32_16x16x32_bf16 v[40:43], v[156:159], v[192:195], v[40:43]
	v_mfma_f32_16x16x32_bf16 v[32:35], v[148:151], v[206:209], v[32:35]
	v_mfma_f32_16x16x32_bf16 v[24:27], v[156:159], v[206:209], v[24:27]
	v_mfma_f32_16x16x32_bf16 v[16:19], v[148:151], v[214:217], v[16:19]
	v_mfma_f32_16x16x32_bf16 v[8:11], v[156:159], v[214:217], v[8:11]
	s_setprio 0
	s_setprio 1
	v_mfma_f32_16x16x32_bf16 v[60:63], v[160:163], v[180:183], v[60:63]
	v_mfma_f32_16x16x32_bf16 v[52:55], v[172:175], v[180:183], v[52:55]
	v_mfma_f32_16x16x32_bf16 v[44:47], v[160:163], v[188:191], v[44:47]
	v_mfma_f32_16x16x32_bf16 v[36:39], v[172:175], v[188:191], v[36:39]
	v_mfma_f32_16x16x32_bf16 v[28:31], v[160:163], v[202:205], v[28:31]
	v_mfma_f32_16x16x32_bf16 v[20:23], v[172:175], v[202:205], v[20:23]
	v_mfma_f32_16x16x32_bf16 v[12:15], v[160:163], v[210:213], v[12:15]
	v_mfma_f32_16x16x32_bf16 v[4:7], v[172:175], v[210:213], v[4:7]
	v_mfma_f32_16x16x32_bf16 v[60:63], v[168:171], v[184:187], v[60:63]
	v_mfma_f32_16x16x32_bf16 v[52:55], v[176:179], v[184:187], v[52:55]
	v_mfma_f32_16x16x32_bf16 v[44:47], v[168:171], v[192:195], v[44:47]
	v_mfma_f32_16x16x32_bf16 v[36:39], v[176:179], v[192:195], v[36:39]
	v_mfma_f32_16x16x32_bf16 v[28:31], v[168:171], v[206:209], v[28:31]
	v_mfma_f32_16x16x32_bf16 v[20:23], v[176:179], v[206:209], v[20:23]
	v_mfma_f32_16x16x32_bf16 v[12:15], v[168:171], v[214:217], v[12:15]
	v_mfma_f32_16x16x32_bf16 v[4:7], v[176:179], v[214:217], v[4:7]
	s_setprio 0
	s_barrier
	s_add_i32 s46, s46, 2
	s_add_u32 s8, s8, 0x100
	s_addc_u32 s9, s9, 0
	s_add_u32 s44, s44, 0x100
	s_addc_u32 s45, s45, 0
	s_cmp_gt_u32 s46, 13
	s_cbranch_scc0 .LBB0_405
	s_and_b64 vcc, exec, s[14:15]
	s_cbranch_vccz .LBB0_408
	s_barrier

; #define PG8_STAGE(bufoff, gbase, voff) do { _Pragma("unroll") for (int _i = 0; _i < 2; ++_i) \
;         __builtin_amdgcn_global_load_lds((const unsigned*)((const char*)(gbase) + (voff)[_i]), (PG8_LAS unsigned*)(lds + (bufoff) + ldsw + _i * 8192), 16, 0, 0); } while (0)
; #define PG8_LDA(dst, b, h) do { _Pragma("unroll") for (int m = 0; m < 4; ++m) _Pragma("unroll") for (int k = 0; k < 2; ++k) dst[m][k] = *(const PG8_LAS bf16x8*)(lds + PG8_SA(b, h) + aoff + m * 2048 + k * 1024); } while (0)
; #define PG8_LDB(dst, b, h) do { _Pragma("unroll") for (int n = 0; n < 2; ++n) _Pragma("unroll") for (int k = 0; k < 2; ++k) dst[n][k] = *(const PG8_LAS bf16x8*)(lds + PG8_SB(b, h) + boff + n * 2048 + k * 1024); } while (0)
; #define PG8_MMA(ai, bj, At, Bt) do { __builtin_amdgcn_s_setprio(1); _Pragma("unroll") for (int m = 0; m < 4; ++m) _Pragma("unroll") for (int n = 0; n < 2; ++n) _Pragma("unroll") for (int k = 0; k < 2; ++k) \
;         acc[ai][bj][m][n] = __builtin_amdgcn_mfma_f32_16x16x32_bf16(Bt[n][k], At[m][k], acc[ai][bj][m][n], 0, 0, 0); __builtin_amdgcn_s_setprio(0); } while (0)
; #define PG8_WAIT_V(n) asm volatile("s_waitcnt vmcnt(" #n ")" ::: "memory")
; #define PG8_BAR __builtin_amdgcn_s_barrier()
; template <class Epi, class Sched, bool ALIGN_EPI = false, bool SP2 = false>
; __device__ __forceinline__ void gemm_phase(PG8_LAS unsigned char* lds, const Gemm g, const Sched& S, const Epi& E) {
;     ...
;         for (int t = 0; t < nt; t += 2) {
;             const bool last = (t == nt - 2);
;             const char* a1 = cA + (size_t)(t + 1) * kstep;
;             const char* a2 = last ? nA : cA + (size_t)(t + 2) * kstep; const char* b2 = last ? nB : cB + (size_t)(t + 2) * kstep;
;             const char* a3 = a2 + kstep; const char* b3 = b2 + kstep;
;             if (last && has_next) S.a_ready(nxt);
;             if constexpr (SP2) {
;             PG8_LDB(B0, 0, 0); PG8_LDB(B1, 0, 1); PG8_SCHED; PG8_LDA(At, 0, 0); PG8_STAGE(PG8_SA(1, 1), a1 + hstep, voffA);
;             PG8_WAIT_V(8); PG8_WAIT_L(0); PG8_BAR; PG8_MMA(0, 0, At, B0); PG8_MMA(0, 1, At, B1); PG8_BAR; PG8_SCHED;
;             PG8_LDA(At, 0, 1); PG8_STAGE(PG8_SB(0, 0), b2, voffB); PG8_STAGE(PG8_SB(0, 1), b2 + hstep, voffB); PG8_STAGE(PG8_SA(0, 0), a2, voffA);
;             PG8_WAIT_V(8); PG8_WAIT_L(0); PG8_BAR; PG8_MMA(1, 0, At, B0); PG8_MMA(1, 1, At, B1); PG8_BAR; PG8_SCHED;
.LBB0_480:
	s_add_u32 s8, s26, 0x100
	s_addc_u32 s9, s27, 0
	s_add_i32 s54, 0, 0x10000
	s_cmp_eq_u32 s53, 40
	s_cselect_b32 s31, s23, s9
	s_cselect_b32 s30, s22, s8
	s_cselect_b32 s29, s25, s45
	s_cselect_b32 s28, s24, s44
	s_add_i32 s55, 0, 0x14000
	v_add_u32_e32 v100, s54, v234
	v_add_u32_e32 v144, s55, v234
	ds_read_b128 v[68:71], v100
	ds_read_b128 v[80:83], v100 offset:1024
	ds_read_b128 v[92:95], v100 offset:2048
	ds_read_b128 v[100:103], v100 offset:3072
	ds_read_b128 v[112:115], v144
	ds_read_b128 v[120:123], v144 offset:1024
	ds_read_b128 v[132:135], v144 offset:2048
	ds_read_b128 v[144:147], v144 offset:3072
	v_lshl_add_u64 v[198:199], s[26:27], 0, v[204:205]
	s_add_i32 m0, s40, 0xc000
	ds_read_b128 v[156:159], v236
	ds_read_b128 v[168:171], v236 offset:1024
	ds_read_b128 v[172:175], v236 offset:2048
	ds_read_b128 v[176:179], v236 offset:3072
	ds_read_b128 v[180:183], v236 offset:4096
	ds_read_b128 v[184:187], v236 offset:5120
	ds_read_b128 v[188:191], v236 offset:6144
	ds_read_b128 v[208:211], v236 offset:7168
	global_load_lds_dwordx4 v[198:199], off
	s_add_i32 m0, s40, 0xe000
	v_lshl_add_u64 v[198:199], s[26:27], 0, v[206:207]
	global_load_lds_dwordx4 v[198:199], off
	s_waitcnt vmcnt(8) lgkmcnt(0)
	s_barrier
	s_setprio 1
	v_mfma_f32_16x16x32_bf16 v[164:167], v[68:71], v[156:159], v[164:167]
	v_mfma_f32_16x16x32_bf16 v[160:163], v[92:95], v[156:159], v[160:163]
	v_mfma_f32_16x16x32_bf16 v[140:143], v[68:71], v[172:175], v[140:143]
	v_mfma_f32_16x16x32_bf16 v[136:139], v[92:95], v[172:175], v[136:139]
	v_mfma_f32_16x16x32_bf16 v[116:119], v[68:71], v[180:183], v[116:119]
	v_mfma_f32_16x16x32_bf16 v[108:111], v[92:95], v[180:183], v[108:111]
	v_mfma_f32_16x16x32_bf16 v[88:91], v[68:71], v[188:191], v[88:91]
	v_mfma_f32_16x16x32_bf16 v[84:87], v[92:95], v[188:191], v[84:87]
	v_mfma_f32_16x16x32_bf16 v[164:167], v[80:83], v[168:171], v[164:167]
	v_mfma_f32_16x16x32_bf16 v[160:163], v[100:103], v[168:171], v[160:163]
	v_mfma_f32_16x16x32_bf16 v[140:143], v[80:83], v[176:179], v[140:143]
	v_mfma_f32_16x16x32_bf16 v[136:139], v[100:103], v[176:179], v[136:139]
	v_mfma_f32_16x16x32_bf16 v[116:119], v[80:83], v[184:187], v[116:119]
	v_mfma_f32_16x16x32_bf16 v[108:111], v[100:103], v[184:187], v[108:111]
	v_mfma_f32_16x16x32_bf16 v[88:91], v[80:83], v[208:211], v[88:91]
	v_mfma_f32_16x16x32_bf16 v[84:87], v[100:103], v[208:211], v[84:87]
	s_setprio 0
	s_setprio 1
	v_mfma_f32_16x16x32_bf16 v[152:155], v[112:115], v[156:159], v[152:155]
	v_mfma_f32_16x16x32_bf16 v[148:151], v[132:135], v[156:159], v[148:151]
	v_mfma_f32_16x16x32_bf16 v[128:131], v[112:115], v[172:175], v[128:131]
	v_mfma_f32_16x16x32_bf16 v[124:127], v[132:135], v[172:175], v[124:127]
	v_mfma_f32_16x16x32_bf16 v[104:107], v[112:115], v[180:183], v[104:107]
	v_mfma_f32_16x16x32_bf16 v[96:99], v[132:135], v[180:183], v[96:99]
	v_mfma_f32_16x16x32_bf16 v[76:79], v[112:115], v[188:191], v[76:79]
	v_mfma_f32_16x16x32_bf16 v[72:75], v[132:135], v[188:191], v[72:75]
	v_mfma_f32_16x16x32_bf16 v[152:155], v[120:123], v[168:171], v[152:155]
	v_mfma_f32_16x16x32_bf16 v[148:151], v[144:147], v[168:171], v[148:151]
	v_mfma_f32_16x16x32_bf16 v[128:131], v[120:123], v[176:179], v[128:131]
	v_mfma_f32_16x16x32_bf16 v[124:127], v[144:147], v[176:179], v[124:127]
	v_mfma_f32_16x16x32_bf16 v[104:107], v[120:123], v[184:187], v[104:107]
	v_mfma_f32_16x16x32_bf16 v[96:99], v[144:147], v[184:187], v[96:99]
	v_mfma_f32_16x16x32_bf16 v[76:79], v[120:123], v[208:211], v[76:79]
	v_mfma_f32_16x16x32_bf16 v[72:75], v[144:147], v[208:211], v[72:75]
	s_setprio 0
	s_barrier
	s_add_i32 s26, s54, s39
	v_lshl_add_u64 v[198:199], s[28:29], 0, v[192:193]
	s_mov_b32 m0, s26
	ds_read_b128 v[156:159], v236 offset:16384
	ds_read_b128 v[168:171], v236 offset:17408
	ds_read_b128 v[172:175], v236 offset:18432
	ds_read_b128 v[176:179], v236 offset:19456
	ds_read_b128 v[180:183], v236 offset:20480
	ds_read_b128 v[184:187], v236 offset:21504
	ds_read_b128 v[188:191], v236 offset:22528
	ds_read_b128 v[208:211], v236 offset:23552
	global_load_lds_dwordx4 v[198:199], off
	s_add_i32 m0, s26, 0x2000
	s_add_u32 s26, s28, 0xb0000
	v_lshl_add_u64 v[212:213], s[28:29], 0, v[202:203]
	s_addc_u32 s27, s29, 0
	s_add_i32 s54, s55, s39
	global_load_lds_dwordx4 v[212:213], off
	v_lshl_add_u64 v[214:215], s[26:27], 0, v[192:193]
	s_mov_b32 m0, s54
	v_lshl_add_u64 v[216:217], s[30:31], 0, v[194:195]
	global_load_lds_dwordx4 v[214:215], off
	s_add_i32 m0, s54, 0x2000
	v_lshl_add_u64 v[214:215], s[26:27], 0, v[202:203]
	global_load_lds_dwordx4 v[214:215], off
	s_mov_b32 m0, s40
	v_lshl_add_u64 v[214:215], s[30:31], 0, v[0:1]
	global_load_lds_dwordx4 v[214:215], off
	s_mov_b32 m0, s41
	s_nop 0
	global_load_lds_dwordx4 v[216:217], off
	s_waitcnt vmcnt(8) lgkmcnt(0)
	s_barrier
; #define PG8_STAGE(bufoff, gbase, voff) do { _Pragma("unroll") for (int _i = 0; _i < 2; ++_i) \
;         __builtin_amdgcn_global_load_lds((const unsigned*)((const char*)(gbase) + (voff)[_i]), (PG8_LAS unsigned*)(lds + (bufoff) + ldsw + _i * 8192), 16, 0, 0); } while (0)
; #define PG8_LDA(dst, b, h) do { _Pragma("unroll") for (int m = 0; m < 4; ++m) _Pragma("unroll") for (int k = 0; k < 2; ++k) dst[m][k] = *(const PG8_LAS bf16x8*)(lds + PG8_SA(b, h) + aoff + m * 2048 + k * 1024); } while (0)
; #define PG8_LDB(dst, b, h) do { _Pragma("unroll") for (int n = 0; n < 2; ++n) _Pragma("unroll") for (int k = 0; k < 2; ++k) dst[n][k] = *(const PG8_LAS bf16x8*)(lds + PG8_SB(b, h) + boff + n * 2048 + k * 1024); } while (0)
; #define PG8_MMA(ai, bj, At, Bt) do { __builtin_amdgcn_s_setprio(1); _Pragma("unroll") for (int m = 0; m < 4; ++m) _Pragma("unroll") for (int n = 0; n < 2; ++n) _Pragma("unroll") for (int k = 0; k < 2; ++k) \
;         acc[ai][bj][m][n] = __builtin_amdgcn_mfma_f32_16x16x32_bf16(Bt[n][k], At[m][k], acc[ai][bj][m][n], 0, 0, 0); __builtin_amdgcn_s_setprio(0); } while (0)
; #define PG8_WAIT_V(n) asm volatile("s_waitcnt vmcnt(" #n ")" ::: "memory")
; #define PG8_WAIT_L(n) asm volatile("s_waitcnt lgkmcnt(" #n ")" ::: "memory")
; #define PG8_BAR __builtin_amdgcn_s_barrier()
; #define PG8_SCHED __builtin_amdgcn_sched_barrier(0)
; template <class Epi, class Sched, bool ALIGN_EPI = false, bool SP2 = false>
; __device__ __forceinline__ void gemm_phase(PG8_LAS unsigned char* lds, const Gemm g, const Sched& S, const Epi& E) {
;     ...
;             PG8_WAIT_V(8); PG8_WAIT_L(0); PG8_BAR; PG8_MMA(1, 0, At, B0); PG8_MMA(1, 1, At, B1); PG8_BAR; PG8_SCHED;
;             PG8_LDB(B0, 1, 0); PG8_LDB(B1, 1, 1); PG8_SCHED; PG8_LDA(At, 1, 0); PG8_STAGE(PG8_SA(0, 1), a2 + hstep, voffA);
;             PG8_WAIT_V(8); PG8_WAIT_L(0); PG8_BAR; PG8_MMA(0, 0, At, B0); PG8_MMA(0, 1, At, B1); PG8_BAR; PG8_SCHED;
	s_setprio 1
	v_mfma_f32_16x16x32_bf16 v[64:67], v[68:71], v[156:159], v[64:67]
	v_mfma_f32_16x16x32_bf16 v[60:63], v[92:95], v[156:159], v[60:63]
	v_mfma_f32_16x16x32_bf16 v[48:51], v[68:71], v[172:175], v[48:51]
	v_mfma_f32_16x16x32_bf16 v[44:47], v[92:95], v[172:175], v[44:47]
	v_mfma_f32_16x16x32_bf16 v[32:35], v[68:71], v[180:183], v[32:35]
	v_mfma_f32_16x16x32_bf16 v[28:31], v[92:95], v[180:183], v[28:31]
	v_mfma_f32_16x16x32_bf16 v[16:19], v[68:71], v[188:191], v[16:19]
	v_mfma_f32_16x16x32_bf16 v[12:15], v[92:95], v[188:191], v[12:15]
	v_mfma_f32_16x16x32_bf16 v[64:67], v[80:83], v[168:171], v[64:67]
	v_mfma_f32_16x16x32_bf16 v[60:63], v[100:103], v[168:171], v[60:63]
	v_mfma_f32_16x16x32_bf16 v[48:51], v[80:83], v[176:179], v[48:51]
	v_mfma_f32_16x16x32_bf16 v[44:47], v[100:103], v[176:179], v[44:47]
	v_mfma_f32_16x16x32_bf16 v[32:35], v[80:83], v[184:187], v[32:35]
	v_mfma_f32_16x16x32_bf16 v[28:31], v[100:103], v[184:187], v[28:31]
	v_mfma_f32_16x16x32_bf16 v[16:19], v[80:83], v[208:211], v[16:19]
	v_mfma_f32_16x16x32_bf16 v[12:15], v[100:103], v[208:211], v[12:15]
	s_setprio 0
	s_setprio 1
	v_mfma_f32_16x16x32_bf16 v[56:59], v[112:115], v[156:159], v[56:59]
	v_mfma_f32_16x16x32_bf16 v[52:55], v[132:135], v[156:159], v[52:55]
	v_mfma_f32_16x16x32_bf16 v[40:43], v[112:115], v[172:175], v[40:43]
	v_mfma_f32_16x16x32_bf16 v[36:39], v[132:135], v[172:175], v[36:39]
	v_mfma_f32_16x16x32_bf16 v[24:27], v[112:115], v[180:183], v[24:27]
	v_mfma_f32_16x16x32_bf16 v[20:23], v[132:135], v[180:183], v[20:23]
	v_mfma_f32_16x16x32_bf16 v[8:11], v[112:115], v[188:191], v[8:11]
	v_mfma_f32_16x16x32_bf16 v[4:7], v[132:135], v[188:191], v[4:7]
	v_mfma_f32_16x16x32_bf16 v[56:59], v[120:123], v[168:171], v[56:59]
	v_mfma_f32_16x16x32_bf16 v[52:55], v[144:147], v[168:171], v[52:55]
	v_mfma_f32_16x16x32_bf16 v[40:43], v[120:123], v[176:179], v[40:43]
	v_mfma_f32_16x16x32_bf16 v[36:39], v[144:147], v[176:179], v[36:39]
	v_mfma_f32_16x16x32_bf16 v[24:27], v[120:123], v[184:187], v[24:27]
	v_mfma_f32_16x16x32_bf16 v[20:23], v[144:147], v[184:187], v[20:23]
	v_mfma_f32_16x16x32_bf16 v[8:11], v[120:123], v[208:211], v[8:11]
	v_mfma_f32_16x16x32_bf16 v[4:7], v[144:147], v[208:211], v[4:7]
	s_setprio 0
	s_barrier
	s_add_i32 s54, 0, 0x18000
	s_add_i32 s55, 0, 0x1c000
	v_add_u32_e32 v100, s54, v234
	v_add_u32_e32 v144, s55, v234
	ds_read_b128 v[68:71], v100
	ds_read_b128 v[80:83], v100 offset:1024
	ds_read_b128 v[92:95], v100 offset:2048
	ds_read_b128 v[100:103], v100 offset:3072
	ds_read_b128 v[112:115], v144
	ds_read_b128 v[120:123], v144 offset:1024
	ds_read_b128 v[132:135], v144 offset:2048
	ds_read_b128 v[144:147], v144 offset:3072
	s_add_u32 s26, s30, 0xb0000
	s_addc_u32 s27, s31, 0
	s_mov_b32 m0, s42
	v_lshl_add_u64 v[218:219], s[26:27], 0, v[0:1]
	ds_read_b128 v[156:159], v236 offset:32768
	ds_read_b128 v[168:171], v236 offset:33792
	ds_read_b128 v[172:175], v236 offset:34816
	ds_read_b128 v[176:179], v236 offset:35840
	ds_read_b128 v[180:183], v236 offset:36864
	ds_read_b128 v[184:187], v236 offset:37888
	ds_read_b128 v[188:191], v236 offset:38912
	ds_read_b128 v[208:211], v236 offset:39936
	global_load_lds_dwordx4 v[218:219], off
	s_mov_b32 m0, s43
	v_lshl_add_u64 v[218:219], s[26:27], 0, v[194:195]
	global_load_lds_dwordx4 v[218:219], off
	s_waitcnt vmcnt(8) lgkmcnt(0)
	s_barrier
	s_setprio 1
	v_mfma_f32_16x16x32_bf16 v[164:167], v[68:71], v[156:159], v[164:167]
	v_mfma_f32_16x16x32_bf16 v[160:163], v[92:95], v[156:159], v[160:163]
	v_mfma_f32_16x16x32_bf16 v[140:143], v[68:71], v[172:175], v[140:143]
	v_mfma_f32_16x16x32_bf16 v[136:139], v[92:95], v[172:175], v[136:139]
	v_mfma_f32_16x16x32_bf16 v[116:119], v[68:71], v[180:183], v[116:119]
	v_mfma_f32_16x16x32_bf16 v[108:111], v[92:95], v[180:183], v[108:111]
	v_mfma_f32_16x16x32_bf16 v[88:91], v[68:71], v[188:191], v[88:91]
	v_mfma_f32_16x16x32_bf16 v[84:87], v[92:95], v[188:191], v[84:87]
	v_mfma_f32_16x16x32_bf16 v[164:167], v[80:83], v[168:171], v[164:167]
	v_mfma_f32_16x16x32_bf16 v[160:163], v[100:103], v[168:171], v[160:163]
	v_mfma_f32_16x16x32_bf16 v[140:143], v[80:83], v[176:179], v[140:143]
	v_mfma_f32_16x16x32_bf16 v[136:139], v[100:103], v[176:179], v[136:139]
	v_mfma_f32_16x16x32_bf16 v[116:119], v[80:83], v[184:187], v[116:119]
	v_mfma_f32_16x16x32_bf16 v[108:111], v[100:103], v[184:187], v[108:111]
	v_mfma_f32_16x16x32_bf16 v[88:91], v[80:83], v[208:211], v[88:91]
	v_mfma_f32_16x16x32_bf16 v[84:87], v[100:103], v[208:211], v[84:87]
	s_setprio 0
	s_setprio 1
	v_mfma_f32_16x16x32_bf16 v[152:155], v[112:115], v[156:159], v[152:155]
	v_mfma_f32_16x16x32_bf16 v[148:151], v[132:135], v[156:159], v[148:151]
	v_mfma_f32_16x16x32_bf16 v[128:131], v[112:115], v[172:175], v[128:131]
	v_mfma_f32_16x16x32_bf16 v[124:127], v[132:135], v[172:175], v[124:127]
	v_mfma_f32_16x16x32_bf16 v[104:107], v[112:115], v[180:183], v[104:107]
	v_mfma_f32_16x16x32_bf16 v[96:99], v[132:135], v[180:183], v[96:99]
	v_mfma_f32_16x16x32_bf16 v[76:79], v[112:115], v[188:191], v[76:79]
	v_mfma_f32_16x16x32_bf16 v[72:75], v[132:135], v[188:191], v[72:75]
	v_mfma_f32_16x16x32_bf16 v[152:155], v[120:123], v[168:171], v[152:155]
	v_mfma_f32_16x16x32_bf16 v[148:151], v[144:147], v[168:171], v[148:151]
	v_mfma_f32_16x16x32_bf16 v[128:131], v[120:123], v[176:179], v[128:131]
	v_mfma_f32_16x16x32_bf16 v[124:127], v[144:147], v[176:179], v[124:127]
	v_mfma_f32_16x16x32_bf16 v[104:107], v[120:123], v[184:187], v[104:107]
	v_mfma_f32_16x16x32_bf16 v[96:99], v[144:147], v[184:187], v[96:99]
	v_mfma_f32_16x16x32_bf16 v[76:79], v[120:123], v[208:211], v[76:79]
	v_mfma_f32_16x16x32_bf16 v[72:75], v[144:147], v[208:211], v[72:75]
	s_setprio 0
	s_barrier
; #define PG8_STAGE(bufoff, gbase, voff) do { _Pragma("unroll") for (int _i = 0; _i < 2; ++_i) \
;         __builtin_amdgcn_global_load_lds((const unsigned*)((const char*)(gbase) + (voff)[_i]), (PG8_LAS unsigned*)(lds + (bufoff) + ldsw + _i * 8192), 16, 0, 0); } while (0)
; #define PG8_LDA(dst, b, h) do { _Pragma("unroll") for (int m = 0; m < 4; ++m) _Pragma("unroll") for (int k = 0; k < 2; ++k) dst[m][k] = *(const PG8_LAS bf16x8*)(lds + PG8_SA(b, h) + aoff + m * 2048 + k * 1024); } while (0)
; #define PG8_MMA(ai, bj, At, Bt) do { __builtin_amdgcn_s_setprio(1); _Pragma("unroll") for (int m = 0; m < 4; ++m) _Pragma("unroll") for (int n = 0; n < 2; ++n) _Pragma("unroll") for (int k = 0; k < 2; ++k) \
;         acc[ai][bj][m][n] = __builtin_amdgcn_mfma_f32_16x16x32_bf16(Bt[n][k], At[m][k], acc[ai][bj][m][n], 0, 0, 0); __builtin_amdgcn_s_setprio(0); } while (0)
; #define PG8_WAIT_V(n) asm volatile("s_waitcnt vmcnt(" #n ")" ::: "memory")
; #define PG8_WAIT_L(n) asm volatile("s_waitcnt lgkmcnt(" #n ")" ::: "memory")
; #define PG8_BAR __builtin_amdgcn_s_barrier()
; #define PG8_SCHED __builtin_amdgcn_sched_barrier(0)
; template <class Epi, class Sched, bool ALIGN_EPI = false, bool SP2 = false>
; __device__ __forceinline__ void gemm_phase(PG8_LAS unsigned char* lds, const Gemm g, const Sched& S, const Epi& E) {
;     ...
;         for (int t = 0; t < nt; t += 2) {
;             const bool last = (t == nt - 2);
;             const char* a1 = cA + (size_t)(t + 1) * kstep;
;             const char* a2 = last ? nA : cA + (size_t)(t + 2) * kstep; const char* b2 = last ? nB : cB + (size_t)(t + 2) * kstep;
;     ...
;             PG8_LDA(At, 1, 1); PG8_STAGE(PG8_SB(1, 0), b3, voffB); PG8_STAGE(PG8_SB(1, 1), b3 + hstep, voffB); PG8_STAGE(PG8_SA(1, 0), a3, voffA);
;             PG8_WAIT_V(8); PG8_WAIT_L(0); PG8_BAR; PG8_MMA(1, 0, At, B0); PG8_MMA(1, 1, At, B1); PG8_BAR; PG8_SCHED;
	s_add_i32 s26, s54, s39
	v_lshl_add_u64 v[198:199], v[198:199], 0, s[82:83]
	s_mov_b32 m0, s26
	ds_read_b128 v[156:159], v236 offset:49152
	ds_read_b128 v[168:171], v236 offset:50176
	ds_read_b128 v[172:175], v236 offset:51200
	ds_read_b128 v[176:179], v236 offset:52224
	ds_read_b128 v[180:183], v236 offset:53248
	ds_read_b128 v[184:187], v236 offset:54272
	ds_read_b128 v[188:191], v236 offset:55296
	ds_read_b128 v[208:211], v236 offset:56320
	global_load_lds_dwordx4 v[198:199], off
	s_add_i32 m0, s26, 0x2000
	s_add_u32 s26, s28, 0xb0080
	v_lshl_add_u64 v[198:199], v[212:213], 0, s[82:83]
	s_addc_u32 s27, s29, 0
	s_add_i32 s28, s55, s39
	global_load_lds_dwordx4 v[198:199], off
	s_mov_b32 m0, s28
	v_lshl_add_u64 v[198:199], s[26:27], 0, v[192:193]
	global_load_lds_dwordx4 v[198:199], off
	s_add_i32 m0, s28, 0x2000
	v_lshl_add_u64 v[198:199], s[26:27], 0, v[202:203]
	global_load_lds_dwordx4 v[198:199], off
	s_mov_b32 m0, s47
	v_lshl_add_u64 v[198:199], v[214:215], 0, s[82:83]
	global_load_lds_dwordx4 v[198:199], off
	s_mov_b32 m0, s48
	v_lshl_add_u64 v[198:199], v[216:217], 0, s[82:83]
	global_load_lds_dwordx4 v[198:199], off
	s_waitcnt vmcnt(8) lgkmcnt(0)
	s_barrier
	s_setprio 1
	v_mfma_f32_16x16x32_bf16 v[64:67], v[68:71], v[156:159], v[64:67]
	v_mfma_f32_16x16x32_bf16 v[60:63], v[92:95], v[156:159], v[60:63]
	v_mfma_f32_16x16x32_bf16 v[48:51], v[68:71], v[172:175], v[48:51]
	v_mfma_f32_16x16x32_bf16 v[44:47], v[92:95], v[172:175], v[44:47]
	v_mfma_f32_16x16x32_bf16 v[32:35], v[68:71], v[180:183], v[32:35]
	v_mfma_f32_16x16x32_bf16 v[28:31], v[92:95], v[180:183], v[28:31]
	v_mfma_f32_16x16x32_bf16 v[16:19], v[68:71], v[188:191], v[16:19]
	v_mfma_f32_16x16x32_bf16 v[12:15], v[92:95], v[188:191], v[12:15]
	v_mfma_f32_16x16x32_bf16 v[64:67], v[80:83], v[168:171], v[64:67]
	v_mfma_f32_16x16x32_bf16 v[60:63], v[100:103], v[168:171], v[60:63]
	v_mfma_f32_16x16x32_bf16 v[48:51], v[80:83], v[176:179], v[48:51]
	v_mfma_f32_16x16x32_bf16 v[44:47], v[100:103], v[176:179], v[44:47]
	v_mfma_f32_16x16x32_bf16 v[32:35], v[80:83], v[184:187], v[32:35]
	v_mfma_f32_16x16x32_bf16 v[28:31], v[100:103], v[184:187], v[28:31]
	v_mfma_f32_16x16x32_bf16 v[16:19], v[80:83], v[208:211], v[16:19]
	v_mfma_f32_16x16x32_bf16 v[12:15], v[100:103], v[208:211], v[12:15]
	s_setprio 0
	s_setprio 1
	v_mfma_f32_16x16x32_bf16 v[56:59], v[112:115], v[156:159], v[56:59]
	v_mfma_f32_16x16x32_bf16 v[52:55], v[132:135], v[156:159], v[52:55]
	v_mfma_f32_16x16x32_bf16 v[40:43], v[112:115], v[172:175], v[40:43]
	v_mfma_f32_16x16x32_bf16 v[36:39], v[132:135], v[172:175], v[36:39]
	v_mfma_f32_16x16x32_bf16 v[24:27], v[112:115], v[180:183], v[24:27]
	v_mfma_f32_16x16x32_bf16 v[20:23], v[132:135], v[180:183], v[20:23]
	v_mfma_f32_16x16x32_bf16 v[8:11], v[112:115], v[188:191], v[8:11]
	v_mfma_f32_16x16x32_bf16 v[4:7], v[132:135], v[188:191], v[4:7]
	v_mfma_f32_16x16x32_bf16 v[56:59], v[120:123], v[168:171], v[56:59]
	v_mfma_f32_16x16x32_bf16 v[52:55], v[144:147], v[168:171], v[52:55]
	v_mfma_f32_16x16x32_bf16 v[40:43], v[120:123], v[176:179], v[40:43]
	v_mfma_f32_16x16x32_bf16 v[36:39], v[144:147], v[176:179], v[36:39]
	v_mfma_f32_16x16x32_bf16 v[24:27], v[120:123], v[184:187], v[24:27]
	v_mfma_f32_16x16x32_bf16 v[20:23], v[144:147], v[184:187], v[20:23]
	v_mfma_f32_16x16x32_bf16 v[8:11], v[120:123], v[208:211], v[8:11]
	v_mfma_f32_16x16x32_bf16 v[4:7], v[144:147], v[208:211], v[4:7]
	s_setprio 0
	s_barrier
	s_add_i32 s53, s53, 2
	s_add_u32 s44, s44, 0x100
	s_addc_u32 s45, s45, 0
	s_cmp_gt_u32 s53, 41
	s_mov_b64 s[26:27], s[8:9]
	s_cbranch_scc0 .LBB0_480
	s_and_b64 vcc, exec, s[20:21]
	s_cbranch_vccz .LBB0_483
	s_barrier
